# GLA scan: one barrier per chunk (double-buffered LDS tiles, scores and state pipelined a chunk apart), global loads three chunks ahead
# baseline (speedup 1.0000x reference)
; __device__ __forceinline__ void gla_scan_phase(const Params& p, int j, bool need_ctx, char* smem, int tid, int bid) {
;   const int lane = tid & 63, wid = tid >> 6, l32 = lane & 31, hi = lane >> 5;
;   char* qbL = smem;
;   char* kinvL = smem + 16384;
;   char* kendT = smem + 32768;
;   char* vT0 = smem + 49152;
;   char* scL = smem + 57344;
;   char* STL = smem + 65536;
;   float* ebend = (float*)(smem + 81920);
;   float* segtot = (float*)(smem + 82432);
;   float* g16L = (float*)(smem + 84480);
;   const u16* P = (const u16*)(p.ws + OFF_S);
;   u16* OF = (u16*)((char*)p.out + OUT_H);
;   u16* OB = (u16*)(p.ws + OFF_S + (size_t)MT * LDP * 2);
;   const float QSCALE = 0.08838834764831845f;
;   for (int unit = bid; unit < 256; unit += gridDim.x) {
;     int dir, dvs, h, b;
;     if (gridDim.x == 256) { const int g = (unit & 7) * 8 + (unit >> 5); dvs = (unit >> 3) & 3; dir = g & 1; h = (g >> 1) & 3; b = g >> 3; }
;     else { dir = unit & 1; dvs = (unit >> 1) & 3; h = (unit >> 3) & 3; b = unit >> 5; }
;     const int dvc = tid & 63, tg = tid >> 6;
;     f32x16 Sacc;
; #pragma unroll
;     for (int r = 0; r < 16; ++r) Sacc[r] = 0.f;
;     __syncthreads();
;     { u32x4 z = {0u, 0u, 0u, 0u}; *(u32x4*)(STL + tid * 32) = z; *(u32x4*)(STL + tid * 32 + 16) = z; }
;     u32x4 qx[2], kx[2]; unsigned kt[16], vv[8]; float ebv = 0.f;
;     const u16* QB = (const u16*)(p.ws + OFF_GQB);
;     const u16* KB2 = (const u16*)((const char*)p.out + OUT_GKB);
;     const float* EBE = (const float*)((const char*)p.out + OUT_EBE);
;     const u16* qsrc = dir ? QB + h * 128 : P + h * 128;
;     const u16* ksrc = dir ? KB2 + h * 128 : P + 512 + h * 128;
;     const long rst = dir ? 512 : LDP;
;     const long sgn = dir ? -1 : 1;
.Lgs_map_done:
	v_readlane_b32 s0, v253, 28
	v_readlane_b32 s1, v253, 29
	v_readlane_b32 s4, v253, 43
	v_readlane_b32 s5, v253, 44
	v_readlane_b32 s8, v253, 45
	v_readlane_b32 s9, v253, 46
	v_readlane_b32 s10, v253, 47
	v_readlane_b32 s11, v253, 48
	v_readlane_b32 s18, v253, 41
	v_readlane_b32 s19, v253, 42
	s_movk_i32 s16, 0x400
	s_cmp_eq_u32 s55, 0
	s_cselect_b32 s34, 0x1840, s16
	s_cselect_b32 s80, 0, 63
	s_cselect_b32 s22, s92, s0
	s_cselect_b32 s23, s93, s1
	s_cselect_b32 s24, s4, s8
	s_cselect_b32 s25, s5, s9
	s_cselect_b32 s30, s12, s18
	s_cselect_b32 s31, s13, s19
	s_lshl_b32 s16, s73, 8
	s_add_u32 s22, s22, s16
	s_addc_u32 s23, s23, 0
	s_add_u32 s24, s24, s16
	s_addc_u32 s25, s25, 0
	s_lshl_b32 s0, s73, 9
	s_lshl_b32 s1, s72, 7
	s_add_u32 s0, s0, s1
	s_add_u32 s30, s30, s0
	s_addc_u32 s31, s31, 0
	s_add_u32 s0, s0, 0x800
	s_add_u32 s26, s92, s0
	s_addc_u32 s27, s93, 0
	s_mul_i32 s4, s55, 0x110000
	s_lshl_b32 s5, s73, 9
	s_add_u32 s4, s4, s5
	s_add_u32 s28, s10, s4
	s_addc_u32 s29, s11, 0
	v_and_b32_e32 v100, 63, v203
	v_lshrrev_b32_e32 v101, 6, v203
	v_and_b32_e32 v102, 31, v203
	v_bfe_u32 v103, v203, 5, 1
	v_and_b32_e32 v104, 15, v203
	v_bfe_u32 v105, v203, 1, 3
	v_readfirstlane_b32 s0, v101
	s_mov_b32 s81, s0
	s_lshr_b32 s1, s0, 1
	s_and_b32 s77, s1, 1
	s_and_b32 s4, s0, 1
	s_cmp_gt_u32 s0, 3
	s_cselect_b32 s76, 2, 0
	s_cmp_eq_u32 s0, 1
	s_cselect_b32 s76, 1, s76
	s_lshl_b32 s5, s4, 13
	s_lshl_b32 s8, s77, 13
	s_add_u32 s9, s5, 0x4000
	s_add_u32 s10, s5, 98304
	s_cmp_eq_u32 s76, 2
	s_cselect_b32 s72, s10, s9
	s_mov_b32 s73, s8
	s_movk_i32 s9, 16384
	s_mov_b32 s10, 40960
	s_cselect_b32 s10, s9, s10
	v_xor_b32_e32 v107, v103, v104
	v_lshlrev_b32_e32 v107, 4, v107
	v_lshl_or_b32 v107, v102, 8, v107
	v_add_u32_e32 v108, s72, v107
	v_add_u32_e32 v109, s73, v107
	s_cmp_eq_u32 s76, 2
	s_cbranch_scc1 .Lgs_akf_done
	v_and_b32_e32 v198, 3, v102
	v_bfe_u32 v199, v102, 2, 2
	v_lshl_or_b32 v198, v198, 2, v199
	v_xor_b32_e32 v198, v103, v198
	v_lshlrev_b32_e32 v198, 4, v198
	v_lshl_or_b32 v198, v102, 8, v198
	v_add_u32_e32 v108, s72, v198
.Lgs_akf_done:
	v_mov_b32_e32 v243, v108
	v_add_u32_e32 v220, s10, v108
	v_mov_b32_e32 v221, v109
	v_xor_b32_e32 v107, v103, v105
	v_lshlrev_b32_e32 v107, 4, v107
	v_lshl_or_b32 v107, v102, 7, v107
	s_lshl_b32 s9, s77, 12
	s_add_u32 s9, s9, 81920
	v_add_u32_e32 v249, s9, v107
	s_lshl_b32 s8, s4, 2
	v_xor_b32_e32 v108, s8, v105
	v_lshlrev_b32_e32 v108, 4, v108
	v_lshl_or_b32 v108, v102, 7, v108
	v_lshl_or_b32 v108, v103, 3, v108
	v_add_u32_e32 v108, s9, v108
	s_cmp_eq_u32 s76, 2
	s_cbranch_scc1 .Lgs_sclw_done
	v_mov_b32_e32 v249, v108
.Lgs_sclw_done:
	s_lshl_b32 s8, s1, 2
	v_xor_b32_e32 v108, s8, v104
	v_lshlrev_b32_e32 v108, 4, v108
	v_lshl_or_b32 v108, v102, 8, v108
	v_lshl_or_b32 v108, v103, 3, v108
	s_add_u32 s9, s5, 98304
	v_add_u32_e32 v250, s9, v108
	s_lshl_b32 s9, s1, 7
	s_add_u32 s9, s9, 131072
	v_lshlrev_b32_e32 v108, 4, v103
	v_add_u32_e32 v252, s9, v108
	v_lshrrev_b32_e32 v106, 3, v203
	v_and_b32_e32 v107, 7, v203
	v_and_b32_e32 v108, 15, v106
	v_xor_b32_e32 v108, v107, v108
	v_lshlrev_b32_e32 v108, 4, v108
	v_lshl_or_b32 v194, v106, 8, v108
	v_xor_b32_e32 v195, 0x80, v194
	v_and_b32_e32 v198, 3, v106
	v_bfe_u32 v199, v106, 2, 2
	v_lshl_or_b32 v198, v198, 2, v199
	v_xor_b32_e32 v198, v107, v198
	v_lshlrev_b32_e32 v198, 4, v198
	v_lshl_or_b32 v143, v106, 8, v198
	v_xor_b32_e32 v144, 0x80, v143
	v_bfe_u32 v198, v106, 1, 1
	v_lshlrev_b32_e32 v198, 2, v198
	v_xor_b32_e32 v198, v107, v198
	v_lshlrev_b32_e32 v198, 4, v198
	v_lshl_or_b32 v196, v106, 7, v198
	v_add_u32_e32 v196, 0x8000, v196
	v_bfe_u32 v108, v203, 4, 1
	v_bfe_u32 v109, v203, 2, 2
	v_and_b32_e32 v198, 3, v203
	v_lshrrev_b32_e32 v199, 1, v198
	v_lshl_or_b32 v199, v108, 1, v199
	v_and_b32_e32 v198, 1, v198
	v_lshlrev_b32_e32 v198, 3, v198
	v_lshl_or_b32 v109, v103, 3, v109
	s_lshl_b32 s9, s1, 2
	v_or_b32_e32 v200, s9, v199
	v_add_u32_e32 v110, 0, v109
	v_and_b32_e32 v140, 3, v110
	v_bfe_u32 v108, v110, 2, 2
	v_lshl_or_b32 v140, v140, 2, v108
	v_xor_b32_e32 v140, v200, v140
	v_lshlrev_b32_e32 v140, 4, v140
	v_lshl_or_b32 v140, v110, 8, v140
	v_or_b32_e32 v140, v140, v198
	v_add_u32_e32 v140, 0x4000, v140
	v_add_u32_e32 v110, 4, v109
	v_and_b32_e32 v141, 3, v110
	v_bfe_u32 v108, v110, 2, 2
	v_lshl_or_b32 v141, v141, 2, v108
	v_xor_b32_e32 v141, v200, v141
	v_lshlrev_b32_e32 v141, 4, v141
	v_lshl_or_b32 v141, v110, 8, v141
	v_or_b32_e32 v141, v141, v198
	v_add_u32_e32 v141, 0x4000, v141
	s_lshl_b32 s9, s4, 2
	v_or_b32_e32 v200, s9, v199
	v_bfe_u32 v108, v109, 1, 1
	v_lshlrev_b32_e32 v108, 2, v108
	v_xor_b32_e32 v200, v200, v108
	v_lshlrev_b32_e32 v142, 4, v200
	v_lshl_or_b32 v142, v109, 7, v142
	v_or_b32_e32 v142, v142, v198
	v_add_u32_e32 v142, 0x8000, v142
	v_lshlrev_b32_e32 v145, 2, v203
	v_add_u32_e32 v197, 131072, v145
	v_xor_b32_e32 v198, s80, v106
	v_mul_lo_u32 v198, v198, s34
	v_lshl_add_u32 v134, v107, 4, v198
	s_movk_i32 s9, 0x1840
	v_xor_b32_e32 v198, s80, v106
	v_mul_lo_u32 v198, v198, s9
	v_lshl_add_u32 v135, v107, 4, v198
	s_cmp_eq_u32 s76, 2
	s_cbranch_scc0 .Lgs_masks
	s_lshl_b32 s9, s77, 5
	v_add_u32_e32 v198, s9, v102
	v_xor_b32_e32 v198, s80, v198
	s_lshl_b32 s9, s4, 6
	v_lshl_add_u32 v108, v103, 4, s9
	v_lshl_add_u32 v204, v198, 11, v108
	s_branch .Lgs_roles_done

; __device__ __forceinline__ void gla_scan_phase(const Params& p, int j, bool need_ctx, char* smem, int tid, int bid) {
;     ...
;     f32x16 Sacc;
; #pragma unroll
;     for (int r = 0; r < 16; ++r) Sacc[r] = 0.f;
;     __syncthreads();
;     { u32x4 z = {0u, 0u, 0u, 0u}; *(u32x4*)(STL + tid * 32) = z; *(u32x4*)(STL + tid * 32 + 16) = z; }
;     u32x4 qx[2], kx[2]; unsigned kt[16], vv[8]; float ebv = 0.f;
;     const u16* QB = (const u16*)(p.ws + OFF_GQB);
;     const u16* KB2 = (const u16*)((const char*)p.out + OUT_GKB);
;     const float* EBE = (const float*)((const char*)p.out + OUT_EBE);
;     const u16* qsrc = dir ? QB + h * 128 : P + h * 128;
;     const u16* ksrc = dir ? KB2 + h * 128 : P + 512 + h * 128;
;     const long rst = dir ? 512 : LDP;
;     const long sgn = dir ? -1 : 1;
;     ...
;     GLA_PREFETCH(0);
;     for (int ci = 0; ci < 68; ++ci) {
;       asm volatile("" : "+v"(tid));
;       const int lane = tid & 63, wid = tid >> 6, l32 = lane & 31, hi = lane >> 5;
;       const int tbg = wid >> 2, kd = (wid & 3) * 32 + l32;
;       const int dvc = tid & 63, tg = tid >> 6;
;       const bool is_ctx = ci < 4; const int c = is_ctx ? ci : ci - 4; const int TT = is_ctx ? CTXL : SEQL;
;       const int base = is_ctx ? ML + b * CTXL : b * SEQL;
;       char* vT = vT0 + (ci & 1) * 40960;
;       {
;         if (tid < 128) ebend[tid] = ebv;
;         const int r = tid >> 3, c0 = tid & 7;
;         *(u32x4*)(qbL + swz256(r, c0)) = qx[0]; *(u32x4*)(qbL + swz256(r, c0 + 8)) = qx[1];
;         *(u32x4*)(kinvL + swz256(r, c0)) = kx[0]; *(u32x4*)(kinvL + swz256(r, c0 + 8)) = kx[1];
;         const int kdt = tid & 127, tgk = tid >> 7;
;         u32x4 w0 = {kt[0] | (kt[1] << 16), kt[2] | (kt[3] << 16), kt[4] | (kt[5] << 16), kt[6] | (kt[7] << 16)};
;         u32x4 w1 = {kt[8] | (kt[9] << 16), kt[10] | (kt[11] << 16), kt[12] | (kt[13] << 16), kt[14] | (kt[15] << 16)};
;         *(u32x4*)(kendT + swz128(kdt, tgk)) = w0;
;         *(u32x4*)(kendT + swz128(kdt, tgk + 4)) = w1;
;         u32x4 wv = {vv[0] | (vv[1] << 16), vv[2] | (vv[3] << 16), vv[4] | (vv[5] << 16), vv[6] | (vv[7] << 16)};
;         *(u32x4*)(vT + swz128(dvc, tg)) = wv;
;       }
.Lgs_roles_done:
	s_waitcnt vmcnt(0) lgkmcnt(0)
	s_barrier
	v_lshlrev_b32_e32 v198, 5, v203
	v_add_u32_e32 v198, 98304, v198
	v_mov_b32_e32 v112, 0
	v_mov_b32_e32 v113, 0
	v_mov_b32_e32 v114, 0
	v_mov_b32_e32 v115, 0
	ds_write_b128 v198, v[112:115]
	ds_write_b128 v198, v[112:115] offset:16
	v_mov_b32_e32 v0, 0
	v_mov_b32_e32 v1, 0
	v_mov_b32_e32 v2, 0
	v_mov_b32_e32 v3, 0
	v_mov_b32_e32 v4, 0
	v_mov_b32_e32 v5, 0
	v_mov_b32_e32 v6, 0
	v_mov_b32_e32 v7, 0
	v_mov_b32_e32 v8, 0
	v_mov_b32_e32 v9, 0
	v_mov_b32_e32 v10, 0
	v_mov_b32_e32 v11, 0
	v_mov_b32_e32 v12, 0
	v_mov_b32_e32 v13, 0
	v_mov_b32_e32 v14, 0
	v_mov_b32_e32 v15, 0
	s_mov_b32 s54, 0
	s_add_i32 s1, s54, -4
	s_cmp_lt_u32 s54, 4
	s_cselect_b32 s0, s54, s1
	s_movk_i32 s5, 0x1000
	s_cselect_b32 s1, 0x100, s5
	s_lshl_b32 s4, s35, 8
	s_add_u32 s4, s4, 0x8000
	s_lshl_b32 s5, s35, 12
	s_cmp_lt_u32 s54, 4
	s_cselect_b32 s4, s4, s5
	s_lshl_b32 s0, s0, 6
	s_sub_u32 s1, s1, 64
	s_sub_u32 s1, s1, s0
	s_cmp_eq_u32 s55, 0
	s_cselect_b32 s0, s0, s1
	s_add_u32 s0, s4, s0
	s_mul_i32 s1, s0, s34
	s_add_u32 s6, s22, s1
	s_addc_u32 s7, s23, 0
	s_add_u32 s8, s24, s1
	s_addc_u32 s9, s25, 0
	s_mul_i32 s1, s0, 0x1840
	s_add_u32 s10, s26, s1
	s_addc_u32 s11, s27, 0
	s_lshr_b32 s1, s0, 6
	s_lshl_b32 s1, s1, 11
	s_add_u32 s18, s28, s1
	s_addc_u32 s19, s29, 0
	global_load_dwordx4 v[112:115], v134, s[6:7]
	global_load_dwordx4 v[116:119], v134, s[6:7] offset:128
	global_load_dwordx4 v[120:123], v134, s[8:9]
	global_load_dwordx4 v[124:127], v134, s[8:9] offset:128
	global_load_dwordx4 v[128:131], v135, s[10:11]
	global_load_dword v132, v145, s[18:19]
	s_mov_b32 s65, 1
	s_add_i32 s1, s65, -4
	s_cmp_lt_u32 s65, 4
	s_cselect_b32 s0, s65, s1
	s_movk_i32 s5, 0x1000
	s_cselect_b32 s1, 0x100, s5
	s_lshl_b32 s4, s35, 8
	s_add_u32 s4, s4, 0x8000
	s_lshl_b32 s5, s35, 12
	s_cmp_lt_u32 s65, 4
	s_cselect_b32 s4, s4, s5
	s_lshl_b32 s0, s0, 6
	s_sub_u32 s1, s1, 64
	s_sub_u32 s1, s1, s0
	s_cmp_eq_u32 s55, 0
	s_cselect_b32 s0, s0, s1
	s_add_u32 s0, s4, s0
	s_mul_i32 s1, s0, s34
	s_add_u32 s6, s22, s1
	s_addc_u32 s7, s23, 0
	s_add_u32 s8, s24, s1
	s_addc_u32 s9, s25, 0
	s_mul_i32 s1, s0, 0x1840
	s_add_u32 s10, s26, s1
	s_addc_u32 s11, s27, 0
	s_lshr_b32 s1, s0, 6
	s_lshl_b32 s1, s1, 11
	s_add_u32 s18, s28, s1
	s_addc_u32 s19, s29, 0
	global_load_dwordx4 v[96:99], v134, s[6:7]
	global_load_dwordx4 v[100:103], v134, s[6:7] offset:128
	global_load_dwordx4 v[104:107], v134, s[8:9]
	global_load_dwordx4 v[108:111], v134, s[8:9] offset:128
	global_load_dwordx4 v[136:139], v135, s[10:11]
	global_load_dword v133, v145, s[18:19]
	s_mov_b32 s65, 2
	s_add_i32 s1, s65, -4
	s_cmp_lt_u32 s65, 4
	s_cselect_b32 s0, s65, s1
	s_movk_i32 s5, 0x1000
	s_cselect_b32 s1, 0x100, s5
	s_lshl_b32 s4, s35, 8
	s_add_u32 s4, s4, 0x8000
	s_lshl_b32 s5, s35, 12
	s_cmp_lt_u32 s65, 4
	s_cselect_b32 s4, s4, s5
	s_lshl_b32 s0, s0, 6
	s_sub_u32 s1, s1, 64
	s_sub_u32 s1, s1, s0
	s_cmp_eq_u32 s55, 0
	s_cselect_b32 s0, s0, s1
	s_add_u32 s0, s4, s0
	s_mul_i32 s1, s0, s34
	s_add_u32 s6, s22, s1
	s_addc_u32 s7, s23, 0
	s_add_u32 s8, s24, s1
	s_addc_u32 s9, s25, 0
	s_mul_i32 s1, s0, 0x1840
	s_add_u32 s10, s26, s1
	s_addc_u32 s11, s27, 0
	s_lshr_b32 s1, s0, 6
	s_lshl_b32 s1, s1, 11
	s_add_u32 s18, s28, s1
	s_addc_u32 s19, s29, 0
	global_load_dwordx4 v[222:225], v134, s[6:7]
	global_load_dwordx4 v[226:229], v134, s[6:7] offset:128
	global_load_dwordx4 v[230:233], v134, s[8:9]
	global_load_dwordx4 v[234:237], v134, s[8:9] offset:128
	global_load_dwordx4 v[244:247], v135, s[10:11]
	global_load_dword v248, v145, s[18:19]
	s_mov_b32 s97, 0
	s_mov_b32 s72, 0
	s_mov_b32 s16, 0
	s_waitcnt vmcnt(12)
	ds_write_b128 v194, v[112:115] offset:0
	ds_write_b128 v195, v[116:119] offset:0
	ds_write_b128 v143, v[120:123] offset:16384
	ds_write_b128 v144, v[124:127] offset:16384
	ds_write_b128 v196, v[128:131] offset:0
	s_cmp_gt_u32 s81, 1
	s_cbranch_scc1 .Lgs_noeb_pro
	ds_write_b32 v197, v132 offset:0
; __device__ __forceinline__ void gla_scan_phase(const Params& p, int j, bool need_ctx, char* smem, int tid, int bid) {
;     ...
;       if (!need_o) {
;       } else if (wid < 4) {
;         const int sb = wid & 1, tb = wid >> 1;
;         if (sb <= tb) {
;           f32x16 sacc;
; #pragma unroll
;           for (int r = 0; r < 16; ++r) sacc[r] = 0.f;
;           bf16x8 av[8], bv8[8];
; #pragma unroll
;           for (int k16 = 0; k16 < 8; ++k16) {
;             av[k16] = *(const bf16x8*)(kinvL + swz256(sb * 32 + l32, k16 * 2 + hi));
;             bv8[k16] = *(const bf16x8*)(qbL + swz256(tb * 32 + l32, k16 * 2 + hi));
;           }
; #pragma unroll
;           for (int k16 = 0; k16 < 8; ++k16) sacc = __builtin_amdgcn_mfma_f32_32x32x16_bf16(av[k16], bv8[k16], sacc, 0, 0, 0);
;           const int t = tb * 32 + l32;
; #pragma unroll
;           for (int rg = 0; rg < 4; ++rg) {
;             const int s0 = sb * 32 + 8 * rg + 4 * hi;
;             const float v0 = (s0 + 0 <= t) ? sacc[rg * 4 + 0] : 0.f, v1 = (s0 + 1 <= t) ? sacc[rg * 4 + 1] : 0.f;
;             const float v2 = (s0 + 2 <= t) ? sacc[rg * 4 + 2] : 0.f, v3 = (s0 + 3 <= t) ? sacc[rg * 4 + 3] : 0.f;
;             u32x2 w = {cvtpk(v0, v1), cvtpk(v2, v3)};
;             *(u32x2*)(scL + swz128(t, s0 >> 3) + (s0 & 7) * 2) = w;
;           }
;         }
;       } else {
;         bf16x8 av[8], bv8[8];
; #pragma unroll
;         for (int k16 = 0; k16 < 8; ++k16) {
;           av[k16] = *(const bf16x8*)(qbL + swz256(tbo * 32 + l32, k16 * 2 + hi));
;           bv8[k16] = *(const bf16x8*)(STL + swz256(dvbo * 32 + l32, k16 * 2 + hi));
;         }
; #pragma unroll
;         for (int k16 = 0; k16 < 8; ++k16) oacc = __builtin_amdgcn_mfma_f32_32x32x16_bf16(av[k16], bv8[k16], oacc, 0, 0, 0);
;       }
;       const int kb = wid >> 1, dvb2 = wid & 1;
;       {
;         bf16x8 av[4], bv4[4];
; #pragma unroll
;         for (int k16 = 0; k16 < 4; ++k16) {
;           av[k16] = *(const bf16x8*)(kendT + swz128(kb * 32 + l32, k16 * 2 + hi));
;           bv4[k16] = *(const bf16x8*)(vT + swz128(dvb2 * 32 + l32, k16 * 2 + hi));
;         }
; #pragma unroll
;         for (int k16 = 0; k16 < 4; ++k16) Sacc = __builtin_amdgcn_mfma_f32_32x32x16_bf16(av[k16], bv4[k16], Sacc, 0, 0, 0);
; #pragma unroll
;         for (int rg = 0; rg < 4; ++rg) {
;           const f32x4 e4 = *(const f32x4*)(ebend + kb * 32 + 8 * rg + 4 * hi);
.Lgs_noeb_pro:
.Lgs_pair:
.Lgs0_chunk:
	s_cmp_gt_u32 s54, 3
	s_cselect_b32 s96, 1, s60
	s_waitcnt lgkmcnt(0)
	s_barrier
	ds_read_b64_tr_b16 v[64:65], v140 offset:0
	ds_read_b64_tr_b16 v[66:67], v141 offset:0
	ds_read_b64_tr_b16 v[80:81], v142 offset:0
	ds_read_b64_tr_b16 v[82:83], v142 offset:512
	ds_read_b64_tr_b16 v[68:69], v140 offset:4096
	ds_read_b64_tr_b16 v[70:71], v141 offset:4096
	ds_read_b64_tr_b16 v[84:85], v142 offset:2048
	ds_read_b64_tr_b16 v[86:87], v142 offset:2560
	ds_read_b64_tr_b16 v[72:73], v140 offset:8192
	ds_read_b64_tr_b16 v[74:75], v141 offset:8192
	ds_read_b64_tr_b16 v[88:89], v142 offset:4096
	ds_read_b64_tr_b16 v[90:91], v142 offset:4608
	s_add_u32 s65, s54, 3
	s_min_u32 s65, s65, 67
	s_add_i32 s1, s65, -4
	s_cmp_lt_u32 s65, 4
	s_cselect_b32 s0, s65, s1
	s_movk_i32 s5, 0x1000
	s_cselect_b32 s1, 0x100, s5
	s_lshl_b32 s4, s35, 8
	s_add_u32 s4, s4, 0x8000
	s_lshl_b32 s5, s35, 12
	s_cmp_lt_u32 s65, 4
	s_cselect_b32 s4, s4, s5
	s_lshl_b32 s0, s0, 6
	s_sub_u32 s1, s1, 64
	s_sub_u32 s1, s1, s0
	s_cmp_eq_u32 s55, 0
	s_cselect_b32 s0, s0, s1
	s_add_u32 s0, s4, s0
	s_mul_i32 s1, s0, s34
	s_add_u32 s6, s22, s1
	s_addc_u32 s7, s23, 0
	s_add_u32 s8, s24, s1
	s_addc_u32 s9, s25, 0
	s_mul_i32 s1, s0, 0x1840
	s_add_u32 s10, s26, s1
	s_addc_u32 s11, s27, 0
	s_lshr_b32 s1, s0, 6
	s_lshl_b32 s1, s1, 11
	s_add_u32 s18, s28, s1
	s_addc_u32 s19, s29, 0
	s_waitcnt lgkmcnt(8)
	v_mfma_f32_32x32x16_bf16 v[0:15], v[64:67], v[80:83], v[0:15]
	ds_read_b64_tr_b16 v[76:77], v140 offset:12288
	ds_read_b64_tr_b16 v[78:79], v141 offset:12288
	ds_read_b64_tr_b16 v[92:93], v142 offset:6144
	ds_read_b64_tr_b16 v[94:95], v142 offset:6656
	s_cmp_eq_u32 s96, 0
	s_cbranch_scc1 .Lgs0_nochain
	s_cmp_eq_u32 s76, 1
	s_cbranch_scc1 .Lgs0_nochain
	s_waitcnt lgkmcnt(8)
	v_mfma_f32_32x32x16_bf16 v[0:15], v[68:71], v[84:87], v[0:15]
	ds_read_b128 v[32:35], v243
	ds_read_b128 v[48:51], v221 offset:0
	v_xor_b32_e32 v198, 32, v243
	v_xor_b32_e32 v199, 32, v221
	ds_read_b128 v[36:39], v198
	ds_read_b128 v[52:55], v199 offset:0
	global_load_dwordx4 v[112:115], v134, s[6:7]
	s_waitcnt lgkmcnt(8)
	v_mfma_f32_32x32x16_bf16 v[0:15], v[72:75], v[88:91], v[0:15]
	v_xor_b32_e32 v198, 64, v243
	v_xor_b32_e32 v199, 64, v221
	ds_read_b128 v[40:43], v198
	ds_read_b128 v[56:59], v199 offset:0
	v_xor_b32_e32 v198, 96, v243
	v_xor_b32_e32 v199, 96, v221
	ds_read_b128 v[44:47], v198
	ds_read_b128 v[60:63], v199 offset:0
	global_load_dwordx4 v[116:119], v134, s[6:7] offset:128
	s_waitcnt lgkmcnt(8)
	v_mfma_f32_32x32x16_bf16 v[0:15], v[76:79], v[92:95], v[0:15]
	global_load_dwordx4 v[120:123], v134, s[8:9]
	s_waitcnt lgkmcnt(6)
	v_mfma_f32_32x32x16_bf16 v[16:31], v[32:35], v[48:51], 0
	v_xor_b32_e32 v198, 128, v243
	v_xor_b32_e32 v199, 128, v221
	ds_read_b128 v[32:35], v198
	ds_read_b128 v[48:51], v199 offset:0
	global_load_dwordx4 v[124:127], v134, s[8:9] offset:128
	s_waitcnt lgkmcnt(6)
	v_mfma_f32_32x32x16_bf16 v[16:31], v[36:39], v[52:55], v[16:31]
	v_xor_b32_e32 v198, 160, v243
	v_xor_b32_e32 v199, 160, v221
	ds_read_b128 v[36:39], v198
	ds_read_b128 v[52:55], v199 offset:0
	global_load_dwordx4 v[128:131], v135, s[10:11]
	s_waitcnt lgkmcnt(6)
	v_mfma_f32_32x32x16_bf16 v[16:31], v[40:43], v[56:59], v[16:31]
	v_xor_b32_e32 v198, 192, v243
	v_xor_b32_e32 v199, 192, v221
	ds_read_b128 v[40:43], v198
	ds_read_b128 v[56:59], v199 offset:0
	global_load_dword v132, v145, s[18:19]
	s_waitcnt lgkmcnt(6)
	v_mfma_f32_32x32x16_bf16 v[16:31], v[44:47], v[60:63], v[16:31]
	v_xor_b32_e32 v198, 224, v243
	v_xor_b32_e32 v199, 224, v221
	ds_read_b128 v[44:47], v198
	ds_read_b128 v[60:63], v199 offset:0
	s_waitcnt lgkmcnt(6)
	v_mfma_f32_32x32x16_bf16 v[16:31], v[32:35], v[48:51], v[16:31]
	ds_read_b128 v[178:181], v252 offset:0
	ds_read_b128 v[182:185], v252 offset:32
	ds_read_b128 v[186:189], v252 offset:64
	ds_read_b128 v[190:193], v252 offset:96
	s_waitcnt lgkmcnt(8)
	v_mfma_f32_32x32x16_bf16 v[16:31], v[36:39], v[52:55], v[16:31]
	s_waitcnt lgkmcnt(6)
	v_mfma_f32_32x32x16_bf16 v[16:31], v[40:43], v[56:59], v[16:31]
	s_waitcnt lgkmcnt(4)
	v_mfma_f32_32x32x16_bf16 v[16:31], v[44:47], v[60:63], v[16:31]
	s_cmp_eq_u32 s16, 0
	s_cbranch_scc1 .Lgs0_scale
	s_cmp_eq_u32 s76, 2
	s_cbranch_scc0 .Lgs0_scale
	v_xor_b32_e32 v198, 32, v249
	ds_read_b128 v[64:67], v249 offset:8192
	ds_read_b128 v[68:71], v198 offset:8192
	s_cmp_eq_u32 s77, 0
	s_cbranch_scc1 .Lgs0_ohalf
	v_xor_b32_e32 v199, 64, v249
	v_xor_b32_e32 v200, 96, v249
	ds_read_b128 v[72:75], v199 offset:8192
	ds_read_b128 v[76:79], v200 offset:8192
	s_waitcnt lgkmcnt(2)
	v_mfma_f32_32x32x16_bf16 v[146:161], v[162:165], v[64:67], v[146:161]
	v_mfma_f32_32x32x16_bf16 v[146:161], v[166:169], v[68:71], v[146:161]
	s_waitcnt lgkmcnt(0)
	v_mfma_f32_32x32x16_bf16 v[146:161], v[170:173], v[72:75], v[146:161]
	v_mfma_f32_32x32x16_bf16 v[146:161], v[174:177], v[76:79], v[146:161]
	s_branch .Lgs0_odone
.Lgs0_ohalf:
	s_waitcnt lgkmcnt(0)
	v_mfma_f32_32x32x16_bf16 v[146:161], v[162:165], v[64:67], v[146:161]
	v_mfma_f32_32x32x16_bf16 v[146:161], v[166:169], v[68:71], v[146:161]

; __device__ __forceinline__ u16 f2bf(float x) { return (u16)(cvtpk(x, 0.f) & 0xffffu); }
; __device__ __forceinline__ void gla_scan_phase(const Params& p, int j, bool need_ctx, char* smem, int tid, int bid) {
;     ...
;       {
;         if (tid < 128) ebend[tid] = ebv;
;         const int r = tid >> 3, c0 = tid & 7;
;         *(u32x4*)(qbL + swz256(r, c0)) = qx[0]; *(u32x4*)(qbL + swz256(r, c0 + 8)) = qx[1];
;         *(u32x4*)(kinvL + swz256(r, c0)) = kx[0]; *(u32x4*)(kinvL + swz256(r, c0 + 8)) = kx[1];
;         const int kdt = tid & 127, tgk = tid >> 7;
;         u32x4 w0 = {kt[0] | (kt[1] << 16), kt[2] | (kt[3] << 16), kt[4] | (kt[5] << 16), kt[6] | (kt[7] << 16)};
;         u32x4 w1 = {kt[8] | (kt[9] << 16), kt[10] | (kt[11] << 16), kt[12] | (kt[13] << 16), kt[14] | (kt[15] << 16)};
;         *(u32x4*)(kendT + swz128(kdt, tgk)) = w0;
;         *(u32x4*)(kendT + swz128(kdt, tgk + 4)) = w1;
;     ...
; #pragma unroll
;         for (int rg = 0; rg < 4; ++rg) {
;           const f32x4 e4 = *(const f32x4*)(ebend + kb * 32 + 8 * rg + 4 * hi);
;           Sacc[rg * 4 + 0] *= e4[0]; Sacc[rg * 4 + 1] *= e4[1]; Sacc[rg * 4 + 2] *= e4[2]; Sacc[rg * 4 + 3] *= e4[3];
;         }
;       }
;       __syncthreads();
;       if (wid >= 4 && need_o) {
; #pragma unroll
;         for (int k16 = 0; k16 < 4; ++k16) {
;           if (k16 < 2 || tbo == 1) {
;             const bf16x8 a = *(const bf16x8*)(scL + swz128(tbo * 32 + l32, k16 * 2 + hi));
;             const bf16x8 bv = *(const bf16x8*)(vT + swz128(dvbo * 32 + l32, k16 * 2 + hi));
;             oacc = __builtin_amdgcn_mfma_f32_32x32x16_bf16(a, bv, oacc, 0, 0, 0);
;           }
;         }
;         if (!is_ctx || need_ctx) {
;           u16* O = dir ? OB : OF;
; #pragma unroll
;           for (int r = 0; r < 16; ++r) {
;             const int pos = c * 64 + tbo * 32 + crow(r, hi);
;             const int tok = dir ? TT - 1 - pos : pos;
;             O[(size_t)(base + tok) * 1024 + h * 256 + dvs * 64 + dvbo * 32 + l32] = f2bf(oacc[r]);
;           }
;         }
;       }
;       {
;         const int dv = dvb2 * 32 + l32;
; #pragma unroll
;         for (int rg = 0; rg < 4; ++rg) {
;           const int k0 = kb * 32 + 8 * rg + 4 * hi;
;           u32x2 w = {cvtpk(Sacc[rg * 4 + 0], Sacc[rg * 4 + 1]), cvtpk(Sacc[rg * 4 + 2], Sacc[rg * 4 + 3])};
;           *(u32x2*)(STL + swz256(dv, k0 >> 3) + (k0 & 7) * 2) = w;
;         }
;       }
.Lgs0_nochain:
	s_waitcnt lgkmcnt(8)
	v_mfma_f32_32x32x16_bf16 v[0:15], v[68:71], v[84:87], v[0:15]
	ds_read_b128 v[178:181], v252 offset:0
	ds_read_b128 v[182:185], v252 offset:32
	ds_read_b128 v[186:189], v252 offset:64
	ds_read_b128 v[190:193], v252 offset:96
	global_load_dwordx4 v[112:115], v134, s[6:7]
	global_load_dwordx4 v[116:119], v134, s[6:7] offset:128
	global_load_dwordx4 v[120:123], v134, s[8:9]
	global_load_dwordx4 v[124:127], v134, s[8:9] offset:128
	global_load_dwordx4 v[128:131], v135, s[10:11]
	global_load_dword v132, v145, s[18:19]
	s_waitcnt lgkmcnt(8)
	v_mfma_f32_32x32x16_bf16 v[0:15], v[72:75], v[88:91], v[0:15]
	s_waitcnt lgkmcnt(4)
	v_mfma_f32_32x32x16_bf16 v[0:15], v[76:79], v[92:95], v[0:15]
	s_nop 7
	s_nop 7
.Lgs0_scale:
	s_waitcnt lgkmcnt(0)
	v_mul_f32_e32 v0, v0, v178
	v_mul_f32_e32 v1, v1, v179
	v_mul_f32_e32 v2, v2, v180
	v_mul_f32_e32 v3, v3, v181
	v_mul_f32_e32 v4, v4, v182
	v_mul_f32_e32 v5, v5, v183
	v_mul_f32_e32 v6, v6, v184
	v_mul_f32_e32 v7, v7, v185
	v_mul_f32_e32 v8, v8, v186
	v_mul_f32_e32 v9, v9, v187
	v_mul_f32_e32 v10, v10, v188
	v_mul_f32_e32 v11, v11, v189
	v_mul_f32_e32 v12, v12, v190
	v_mul_f32_e32 v13, v13, v191
	v_mul_f32_e32 v14, v14, v192
	v_mul_f32_e32 v15, v15, v193
	v_cvt_pk_bf16_f32 v178, v0, v1
	v_cvt_pk_bf16_f32 v179, v2, v3
	v_cvt_pk_bf16_f32 v180, v4, v5
	v_cvt_pk_bf16_f32 v181, v6, v7
	v_cvt_pk_bf16_f32 v182, v8, v9
	v_cvt_pk_bf16_f32 v183, v10, v11
	v_cvt_pk_bf16_f32 v184, v12, v13
	v_cvt_pk_bf16_f32 v185, v14, v15
	v_xor_b32_e32 v198, 16, v250
	v_xor_b32_e32 v199, 32, v250
	v_xor_b32_e32 v200, 48, v250
	ds_write_b64 v250, v[178:179] offset:16384
	ds_write_b64 v198, v[180:181] offset:16384
	ds_write_b64 v199, v[182:183] offset:16384
	ds_write_b64 v200, v[184:185] offset:16384
	s_add_u32 s0, s97, s72
	s_cmp_eq_u32 s0, 4
	s_cbranch_scc1 .Lgs0_w16
	s_waitcnt vmcnt(12)
	s_branch .Lgs0_wd
.Lgs0_w16:
	s_waitcnt vmcnt(16)
.Lgs0_wd:
	ds_write_b128 v194, v[96:99] offset:40960
	ds_write_b128 v195, v[100:103] offset:40960
	ds_write_b128 v143, v[104:107] offset:57344
	ds_write_b128 v144, v[108:111] offset:57344
	ds_write_b128 v196, v[136:139] offset:40960
	s_cmp_gt_u32 s81, 1
	s_cbranch_scc1 .Lgs_noeb_b0
	ds_write_b32 v197, v133 offset:512
.Lgs_noeb_b0:
	s_mov_b32 s72, s97
	s_mov_b32 s97, 0
	s_cmp_eq_u32 s76, 1
	s_cbranch_scc1 .Lgs0_next
	s_cmp_eq_u32 s76, 2
	s_cbranch_scc1 .Lgs0_otail
	s_cmp_eq_u32 s96, 0
	s_cbranch_scc1 .Lgs0_next
	v_and_b32_e32 v16, v204, v16
	v_and_b32_e32 v17, v205, v17
	v_and_b32_e32 v18, v206, v18
	v_and_b32_e32 v19, v207, v19
	v_and_b32_e32 v20, v208, v20
	v_and_b32_e32 v21, v209, v21
	v_and_b32_e32 v22, v210, v22
	v_and_b32_e32 v23, v211, v23
	v_and_b32_e32 v24, v212, v24
	v_and_b32_e32 v25, v213, v25
	v_and_b32_e32 v26, v214, v26
	v_and_b32_e32 v27, v215, v27
	v_and_b32_e32 v28, v216, v28
	v_and_b32_e32 v29, v217, v29
	v_and_b32_e32 v30, v218, v30
	v_and_b32_e32 v31, v219, v31
	v_cvt_pk_bf16_f32 v32, v16, v17
	v_cvt_pk_bf16_f32 v33, v18, v19
	v_cvt_pk_bf16_f32 v34, v20, v21
	v_cvt_pk_bf16_f32 v35, v22, v23
	v_cvt_pk_bf16_f32 v36, v24, v25
	v_cvt_pk_bf16_f32 v37, v26, v27
	v_cvt_pk_bf16_f32 v38, v28, v29
	v_cvt_pk_bf16_f32 v39, v30, v31
	v_xor_b32_e32 v198, 16, v249
	v_xor_b32_e32 v199, 32, v249
	v_xor_b32_e32 v200, 48, v249
	ds_write_b64 v249, v[32:33] offset:0
	ds_write_b64 v198, v[34:35] offset:0
	ds_write_b64 v199, v[36:37] offset:0
	ds_write_b64 v200, v[38:39] offset:0
	s_branch .Lgs0_next
.Lgs0_otail:
	s_cmp_eq_u32 s16, 0
	s_cbranch_scc1 .Lgs0_next
	s_add_i32 s65, s54, -1
	s_add_i32 s1, s65, -4
	s_cmp_lt_u32 s65, 4
	s_cselect_b32 s0, s65, s1
	s_movk_i32 s5, 0x1000
	s_cselect_b32 s1, 0x100, s5
	s_lshl_b32 s4, s35, 8
	s_add_u32 s4, s4, 0x8000
	s_lshl_b32 s5, s35, 12
	s_cmp_lt_u32 s65, 4
	s_cselect_b32 s4, s4, s5
	s_lshl_b32 s0, s0, 6
	s_sub_u32 s1, s1, 64
	s_sub_u32 s1, s1, s0
	s_cmp_eq_u32 s55, 0
	s_cselect_b32 s0, s0, s1
	s_add_u32 s0, s4, s0
	s_lshl_b32 s1, s0, 11
	s_add_u32 s20, s30, s1
	s_addc_u32 s21, s31, 0
	v_cvt_pk_bf16_f32 v186, v146, v147
	v_cvt_pk_bf16_f32 v187, v148, v149
	v_cvt_pk_bf16_f32 v188, v150, v151
	v_cvt_pk_bf16_f32 v189, v152, v153
	v_cvt_pk_bf16_f32 v190, v154, v155
	v_cvt_pk_bf16_f32 v191, v156, v157
	v_cvt_pk_bf16_f32 v192, v158, v159
	v_cvt_pk_bf16_f32 v193, v160, v161
	s_nop 0
	v_permlane32_swap_b32_e32 v186, v188
	v_permlane32_swap_b32_e32 v187, v189
	v_permlane32_swap_b32_e32 v190, v192
	v_permlane32_swap_b32_e32 v191, v193
	global_store_dwordx4 v204, v[186:189], s[20:21]
	global_store_dwordx4 v204, v[190:193], s[20:21] offset:32
	s_mov_b32 s97, 2
.Lgs0_next:
	s_mov_b32 s16, s96
	s_add_u32 s54, s54, 1
; __device__ __forceinline__ void gla_scan_phase(const Params& p, int j, bool need_ctx, char* smem, int tid, int bid) {
;     ...
;       if (!need_o) {
;       } else if (wid < 4) {
;         const int sb = wid & 1, tb = wid >> 1;
;         if (sb <= tb) {
;           f32x16 sacc;
; #pragma unroll
;           for (int r = 0; r < 16; ++r) sacc[r] = 0.f;
;           bf16x8 av[8], bv8[8];
; #pragma unroll
;           for (int k16 = 0; k16 < 8; ++k16) {
;             av[k16] = *(const bf16x8*)(kinvL + swz256(sb * 32 + l32, k16 * 2 + hi));
;             bv8[k16] = *(const bf16x8*)(qbL + swz256(tb * 32 + l32, k16 * 2 + hi));
;           }
; #pragma unroll
;           for (int k16 = 0; k16 < 8; ++k16) sacc = __builtin_amdgcn_mfma_f32_32x32x16_bf16(av[k16], bv8[k16], sacc, 0, 0, 0);
;           const int t = tb * 32 + l32;
; #pragma unroll
;           for (int rg = 0; rg < 4; ++rg) {
;             const int s0 = sb * 32 + 8 * rg + 4 * hi;
;             const float v0 = (s0 + 0 <= t) ? sacc[rg * 4 + 0] : 0.f, v1 = (s0 + 1 <= t) ? sacc[rg * 4 + 1] : 0.f;
;             const float v2 = (s0 + 2 <= t) ? sacc[rg * 4 + 2] : 0.f, v3 = (s0 + 3 <= t) ? sacc[rg * 4 + 3] : 0.f;
;             u32x2 w = {cvtpk(v0, v1), cvtpk(v2, v3)};
;             *(u32x2*)(scL + swz128(t, s0 >> 3) + (s0 & 7) * 2) = w;
;           }
;         }
;       } else {
;         bf16x8 av[8], bv8[8];
; #pragma unroll
;         for (int k16 = 0; k16 < 8; ++k16) {
;           av[k16] = *(const bf16x8*)(qbL + swz256(tbo * 32 + l32, k16 * 2 + hi));
;           bv8[k16] = *(const bf16x8*)(STL + swz256(dvbo * 32 + l32, k16 * 2 + hi));
;         }
; #pragma unroll
;         for (int k16 = 0; k16 < 8; ++k16) oacc = __builtin_amdgcn_mfma_f32_32x32x16_bf16(av[k16], bv8[k16], oacc, 0, 0, 0);
;       }
;       const int kb = wid >> 1, dvb2 = wid & 1;
;       {
;         bf16x8 av[4], bv4[4];
; #pragma unroll
;         for (int k16 = 0; k16 < 4; ++k16) {
;           av[k16] = *(const bf16x8*)(kendT + swz128(kb * 32 + l32, k16 * 2 + hi));
;           bv4[k16] = *(const bf16x8*)(vT + swz128(dvb2 * 32 + l32, k16 * 2 + hi));
;         }
; #pragma unroll
;         for (int k16 = 0; k16 < 4; ++k16) Sacc = __builtin_amdgcn_mfma_f32_32x32x16_bf16(av[k16], bv4[k16], Sacc, 0, 0, 0);
; #pragma unroll
;         for (int rg = 0; rg < 4; ++rg) {
;           const f32x4 e4 = *(const f32x4*)(ebend + kb * 32 + 8 * rg + 4 * hi);
.Lgs1_chunk:
	s_cmp_gt_u32 s54, 3
	s_cselect_b32 s96, 1, s60
	s_waitcnt lgkmcnt(0)
	s_barrier
	ds_read_b64_tr_b16 v[64:65], v140 offset:40960
	ds_read_b64_tr_b16 v[66:67], v141 offset:40960
	ds_read_b64_tr_b16 v[162:163], v142 offset:40960
	ds_read_b64_tr_b16 v[164:165], v142 offset:41472
	ds_read_b64_tr_b16 v[68:69], v140 offset:45056
	ds_read_b64_tr_b16 v[70:71], v141 offset:45056
	ds_read_b64_tr_b16 v[166:167], v142 offset:43008
	ds_read_b64_tr_b16 v[168:169], v142 offset:43520
	ds_read_b64_tr_b16 v[72:73], v140 offset:49152
	ds_read_b64_tr_b16 v[74:75], v141 offset:49152
	ds_read_b64_tr_b16 v[170:171], v142 offset:45056
	ds_read_b64_tr_b16 v[172:173], v142 offset:45568
	s_add_u32 s65, s54, 3
	s_min_u32 s65, s65, 67
	s_add_i32 s1, s65, -4
	s_cmp_lt_u32 s65, 4
	s_cselect_b32 s0, s65, s1
	s_movk_i32 s5, 0x1000
	s_cselect_b32 s1, 0x100, s5
	s_lshl_b32 s4, s35, 8
	s_add_u32 s4, s4, 0x8000
	s_lshl_b32 s5, s35, 12
	s_cmp_lt_u32 s65, 4
	s_cselect_b32 s4, s4, s5
	s_lshl_b32 s0, s0, 6
	s_sub_u32 s1, s1, 64
	s_sub_u32 s1, s1, s0
	s_cmp_eq_u32 s55, 0
	s_cselect_b32 s0, s0, s1
	s_add_u32 s0, s4, s0
	s_mul_i32 s1, s0, s34
	s_add_u32 s6, s22, s1
	s_addc_u32 s7, s23, 0
	s_add_u32 s8, s24, s1
	s_addc_u32 s9, s25, 0
	s_mul_i32 s1, s0, 0x1840
	s_add_u32 s10, s26, s1
	s_addc_u32 s11, s27, 0
	s_lshr_b32 s1, s0, 6
	s_lshl_b32 s1, s1, 11
	s_add_u32 s18, s28, s1
	s_addc_u32 s19, s29, 0
	s_waitcnt lgkmcnt(8)
	v_mfma_f32_32x32x16_bf16 v[0:15], v[64:67], v[162:165], v[0:15]
	ds_read_b64_tr_b16 v[76:77], v140 offset:53248
	ds_read_b64_tr_b16 v[78:79], v141 offset:53248
	ds_read_b64_tr_b16 v[174:175], v142 offset:47104
	ds_read_b64_tr_b16 v[176:177], v142 offset:47616
	s_cmp_eq_u32 s96, 0
	s_cbranch_scc1 .Lgs1_nochain
	s_cmp_eq_u32 s76, 1
	s_cbranch_scc1 .Lgs1_nochain
	s_waitcnt lgkmcnt(8)
	v_mfma_f32_32x32x16_bf16 v[0:15], v[68:71], v[166:169], v[0:15]
	ds_read_b128 v[32:35], v220
	ds_read_b128 v[48:51], v221 offset:40960
	v_xor_b32_e32 v198, 32, v220
	v_xor_b32_e32 v199, 32, v221
	ds_read_b128 v[36:39], v198
	ds_read_b128 v[52:55], v199 offset:40960
	global_load_dwordx4 v[96:99], v134, s[6:7]
	s_waitcnt lgkmcnt(8)
	v_mfma_f32_32x32x16_bf16 v[0:15], v[72:75], v[170:173], v[0:15]
	v_xor_b32_e32 v198, 64, v220
	v_xor_b32_e32 v199, 64, v221
	ds_read_b128 v[40:43], v198
	ds_read_b128 v[56:59], v199 offset:40960
	v_xor_b32_e32 v198, 96, v220
	v_xor_b32_e32 v199, 96, v221
	ds_read_b128 v[44:47], v198
	ds_read_b128 v[60:63], v199 offset:40960
	global_load_dwordx4 v[100:103], v134, s[6:7] offset:128
	s_waitcnt lgkmcnt(8)
	v_mfma_f32_32x32x16_bf16 v[0:15], v[76:79], v[174:177], v[0:15]
	global_load_dwordx4 v[104:107], v134, s[8:9]
	s_waitcnt lgkmcnt(6)
	v_mfma_f32_32x32x16_bf16 v[146:161], v[32:35], v[48:51], 0
	v_xor_b32_e32 v198, 128, v220
	v_xor_b32_e32 v199, 128, v221
	ds_read_b128 v[32:35], v198
	ds_read_b128 v[48:51], v199 offset:40960
	global_load_dwordx4 v[108:111], v134, s[8:9] offset:128
	s_waitcnt lgkmcnt(6)
	v_mfma_f32_32x32x16_bf16 v[146:161], v[36:39], v[52:55], v[146:161]
	v_xor_b32_e32 v198, 160, v220
	v_xor_b32_e32 v199, 160, v221
	ds_read_b128 v[36:39], v198
	ds_read_b128 v[52:55], v199 offset:40960
	global_load_dwordx4 v[136:139], v135, s[10:11]
	s_waitcnt lgkmcnt(6)
	v_mfma_f32_32x32x16_bf16 v[146:161], v[40:43], v[56:59], v[146:161]
	v_xor_b32_e32 v198, 192, v220
	v_xor_b32_e32 v199, 192, v221
	ds_read_b128 v[40:43], v198
	ds_read_b128 v[56:59], v199 offset:40960
	global_load_dword v133, v145, s[18:19]
	s_waitcnt lgkmcnt(6)
	v_mfma_f32_32x32x16_bf16 v[146:161], v[44:47], v[60:63], v[146:161]
	v_xor_b32_e32 v198, 224, v220
	v_xor_b32_e32 v199, 224, v221
	ds_read_b128 v[44:47], v198
	ds_read_b128 v[60:63], v199 offset:40960
	s_waitcnt lgkmcnt(6)
	v_mfma_f32_32x32x16_bf16 v[146:161], v[32:35], v[48:51], v[146:161]
	ds_read_b128 v[178:181], v252 offset:512
	ds_read_b128 v[182:185], v252 offset:544
	ds_read_b128 v[186:189], v252 offset:576
	ds_read_b128 v[190:193], v252 offset:608
	s_waitcnt lgkmcnt(8)
	v_mfma_f32_32x32x16_bf16 v[146:161], v[36:39], v[52:55], v[146:161]
	s_waitcnt lgkmcnt(6)
	v_mfma_f32_32x32x16_bf16 v[146:161], v[40:43], v[56:59], v[146:161]
	s_waitcnt lgkmcnt(4)
	v_mfma_f32_32x32x16_bf16 v[146:161], v[44:47], v[60:63], v[146:161]
	s_cmp_eq_u32 s16, 0
	s_cbranch_scc1 .Lgs1_scale
	s_cmp_eq_u32 s76, 2
	s_cbranch_scc0 .Lgs1_scale
	v_xor_b32_e32 v198, 32, v249
	ds_read_b128 v[64:67], v249 offset:0
	ds_read_b128 v[68:71], v198 offset:0
	s_cmp_eq_u32 s77, 0
	s_cbranch_scc1 .Lgs1_ohalf
	v_xor_b32_e32 v199, 64, v249
	v_xor_b32_e32 v200, 96, v249
	ds_read_b128 v[72:75], v199 offset:0
	ds_read_b128 v[76:79], v200 offset:0
	s_waitcnt lgkmcnt(2)
	v_mfma_f32_32x32x16_bf16 v[16:31], v[80:83], v[64:67], v[16:31]
	v_mfma_f32_32x32x16_bf16 v[16:31], v[84:87], v[68:71], v[16:31]
	s_waitcnt lgkmcnt(0)
	v_mfma_f32_32x32x16_bf16 v[16:31], v[88:91], v[72:75], v[16:31]
	v_mfma_f32_32x32x16_bf16 v[16:31], v[92:95], v[76:79], v[16:31]
	s_branch .Lgs1_odone
.Lgs1_ohalf:
	s_waitcnt lgkmcnt(0)
	v_mfma_f32_32x32x16_bf16 v[16:31], v[80:83], v[64:67], v[16:31]
	v_mfma_f32_32x32x16_bf16 v[16:31], v[84:87], v[68:71], v[16:31]

; __device__ __forceinline__ void gla_scan_phase(const Params& p, int j, bool need_ctx, char* smem, int tid, int bid) {
;     ...
;           av[k16] = *(const bf16x8*)(kendT + swz128(kb * 32 + l32, k16 * 2 + hi));
;           bv4[k16] = *(const bf16x8*)(vT + swz128(dvb2 * 32 + l32, k16 * 2 + hi));
;         }
; #pragma unroll
;         for (int k16 = 0; k16 < 4; ++k16) Sacc = __builtin_amdgcn_mfma_f32_32x32x16_bf16(av[k16], bv4[k16], Sacc, 0, 0, 0);
; #pragma unroll
;         for (int rg = 0; rg < 4; ++rg) {
;           const f32x4 e4 = *(const f32x4*)(ebend + kb * 32 + 8 * rg + 4 * hi);
;           Sacc[rg * 4 + 0] *= e4[0]; Sacc[rg * 4 + 1] *= e4[1]; Sacc[rg * 4 + 2] *= e4[2]; Sacc[rg * 4 + 3] *= e4[3];
;         }
;       }
;     ...
;       {
;         const int dv = dvb2 * 32 + l32;
; #pragma unroll
;         for (int rg = 0; rg < 4; ++rg) {
;           const int k0 = kb * 32 + 8 * rg + 4 * hi;
;           u32x2 w = {cvtpk(Sacc[rg * 4 + 0], Sacc[rg * 4 + 1]), cvtpk(Sacc[rg * 4 + 2], Sacc[rg * 4 + 3])};
;           *(u32x2*)(STL + swz256(dv, k0 >> 3) + (k0 & 7) * 2) = w;
;         }
;       }
.Lgs1_nochain:
	s_waitcnt lgkmcnt(8)
	v_mfma_f32_32x32x16_bf16 v[0:15], v[68:71], v[166:169], v[0:15]
	ds_read_b128 v[178:181], v252 offset:512
	ds_read_b128 v[182:185], v252 offset:544
	ds_read_b128 v[186:189], v252 offset:576
	ds_read_b128 v[190:193], v252 offset:608
	global_load_dwordx4 v[96:99], v134, s[6:7]
	global_load_dwordx4 v[100:103], v134, s[6:7] offset:128
	global_load_dwordx4 v[104:107], v134, s[8:9]
	global_load_dwordx4 v[108:111], v134, s[8:9] offset:128
	global_load_dwordx4 v[136:139], v135, s[10:11]
	global_load_dword v133, v145, s[18:19]
	s_waitcnt lgkmcnt(8)
	v_mfma_f32_32x32x16_bf16 v[0:15], v[72:75], v[170:173], v[0:15]
	s_waitcnt lgkmcnt(4)
	v_mfma_f32_32x32x16_bf16 v[0:15], v[76:79], v[174:177], v[0:15]
	s_nop 7
	s_nop 7
.Lgs1_scale:
	s_waitcnt lgkmcnt(0)
	v_mul_f32_e32 v0, v0, v178
	v_mul_f32_e32 v1, v1, v179
	v_mul_f32_e32 v2, v2, v180
	v_mul_f32_e32 v3, v3, v181
	v_mul_f32_e32 v4, v4, v182
	v_mul_f32_e32 v5, v5, v183
	v_mul_f32_e32 v6, v6, v184
	v_mul_f32_e32 v7, v7, v185
	v_mul_f32_e32 v8, v8, v186
	v_mul_f32_e32 v9, v9, v187
	v_mul_f32_e32 v10, v10, v188
	v_mul_f32_e32 v11, v11, v189
	v_mul_f32_e32 v12, v12, v190
	v_mul_f32_e32 v13, v13, v191
	v_mul_f32_e32 v14, v14, v192
	v_mul_f32_e32 v15, v15, v193
	v_cvt_pk_bf16_f32 v178, v0, v1
	v_cvt_pk_bf16_f32 v179, v2, v3
	v_cvt_pk_bf16_f32 v180, v4, v5
	v_cvt_pk_bf16_f32 v181, v6, v7
	v_cvt_pk_bf16_f32 v182, v8, v9
	v_cvt_pk_bf16_f32 v183, v10, v11
	v_cvt_pk_bf16_f32 v184, v12, v13
	v_cvt_pk_bf16_f32 v185, v14, v15
	v_xor_b32_e32 v198, 16, v250
	v_xor_b32_e32 v199, 32, v250
	v_xor_b32_e32 v200, 48, v250
	ds_write_b64 v250, v[178:179] offset:0
	ds_write_b64 v198, v[180:181] offset:0
	ds_write_b64 v199, v[182:183] offset:0
	ds_write_b64 v200, v[184:185] offset:0
	s_add_u32 s0, s97, s72
	s_cmp_eq_u32 s0, 4
	s_cbranch_scc1 .Lgs1_w16
	s_waitcnt vmcnt(12)
	s_branch .Lgs1_wd

; __device__ __forceinline__ void gla_scan_phase(const Params& p, int j, bool need_ctx, char* smem, int tid, int bid) {
;     ...
;           const int t = tb * 32 + l32;
; #pragma unroll
;           for (int rg = 0; rg < 4; ++rg) {
;             const int s0 = sb * 32 + 8 * rg + 4 * hi;
;             const float v0 = (s0 + 0 <= t) ? sacc[rg * 4 + 0] : 0.f, v1 = (s0 + 1 <= t) ? sacc[rg * 4 + 1] : 0.f;
;             const float v2 = (s0 + 2 <= t) ? sacc[rg * 4 + 2] : 0.f, v3 = (s0 + 3 <= t) ? sacc[rg * 4 + 3] : 0.f;
;             u32x2 w = {cvtpk(v0, v1), cvtpk(v2, v3)};
;             *(u32x2*)(scL + swz128(t, s0 >> 3) + (s0 & 7) * 2) = w;
;           }
;         }
;       } else {
;         bf16x8 av[8], bv8[8];
; #pragma unroll
;         for (int k16 = 0; k16 < 8; ++k16) {
;           av[k16] = *(const bf16x8*)(qbL + swz256(tbo * 32 + l32, k16 * 2 + hi));
;           bv8[k16] = *(const bf16x8*)(STL + swz256(dvbo * 32 + l32, k16 * 2 + hi));
;         }
; #pragma unroll
;         for (int k16 = 0; k16 < 8; ++k16) oacc = __builtin_amdgcn_mfma_f32_32x32x16_bf16(av[k16], bv8[k16], oacc, 0, 0, 0);
;       }
;       const int kb = wid >> 1, dvb2 = wid & 1;
;       {
;         bf16x8 av[4], bv4[4];
; #pragma unroll
;         for (int k16 = 0; k16 < 4; ++k16) {
;           av[k16] = *(const bf16x8*)(kendT + swz128(kb * 32 + l32, k16 * 2 + hi));
;           bv4[k16] = *(const bf16x8*)(vT + swz128(dvb2 * 32 + l32, k16 * 2 + hi));
;         }
; #pragma unroll
;         for (int k16 = 0; k16 < 4; ++k16) Sacc = __builtin_amdgcn_mfma_f32_32x32x16_bf16(av[k16], bv4[k16], Sacc, 0, 0, 0);
; #pragma unroll
;         for (int rg = 0; rg < 4; ++rg) {
;           const f32x4 e4 = *(const f32x4*)(ebend + kb * 32 + 8 * rg + 4 * hi);
;           Sacc[rg * 4 + 0] *= e4[0]; Sacc[rg * 4 + 1] *= e4[1]; Sacc[rg * 4 + 2] *= e4[2]; Sacc[rg * 4 + 3] *= e4[3];
;         }
;       }
;       __syncthreads();
;       if (wid >= 4 && need_o) {
; #pragma unroll
;         for (int k16 = 0; k16 < 4; ++k16) {
;           if (k16 < 2 || tbo == 1) {
;             const bf16x8 a = *(const bf16x8*)(scL + swz128(tbo * 32 + l32, k16 * 2 + hi));
;             const bf16x8 bv = *(const bf16x8*)(vT + swz128(dvbo * 32 + l32, k16 * 2 + hi));
;             oacc = __builtin_amdgcn_mfma_f32_32x32x16_bf16(a, bv, oacc, 0, 0, 0);
;           }
;         }
;         if (!is_ctx || need_ctx) {
.Lgs1_wd:
	ds_write_b128 v194, v[222:225] offset:0
	ds_write_b128 v195, v[226:229] offset:0
	ds_write_b128 v143, v[230:233] offset:16384
	ds_write_b128 v144, v[234:237] offset:16384
	ds_write_b128 v196, v[244:247] offset:0
	s_cmp_gt_u32 s81, 1
	s_cbranch_scc1 .Lgs_noeb_b1
	ds_write_b32 v197, v248 offset:0
.Lgs_noeb_b1:
	s_mov_b32 s72, s97
	s_mov_b32 s97, 0
	s_cmp_eq_u32 s76, 1
	s_cbranch_scc1 .Lgs1_next
	s_cmp_eq_u32 s76, 2
	s_cbranch_scc1 .Lgs1_otail
	s_cmp_eq_u32 s96, 0
	s_cbranch_scc1 .Lgs1_next
	v_and_b32_e32 v146, v204, v146
	v_and_b32_e32 v147, v205, v147
	v_and_b32_e32 v148, v206, v148
	v_and_b32_e32 v149, v207, v149
	v_and_b32_e32 v150, v208, v150
	v_and_b32_e32 v151, v209, v151
	v_and_b32_e32 v152, v210, v152
	v_and_b32_e32 v153, v211, v153
	v_and_b32_e32 v154, v212, v154
	v_and_b32_e32 v155, v213, v155
	v_and_b32_e32 v156, v214, v156
	v_and_b32_e32 v157, v215, v157
	v_and_b32_e32 v158, v216, v158
	v_and_b32_e32 v159, v217, v159
	v_and_b32_e32 v160, v218, v160
	v_and_b32_e32 v161, v219, v161
	v_cvt_pk_bf16_f32 v32, v146, v147
	v_cvt_pk_bf16_f32 v33, v148, v149
	v_cvt_pk_bf16_f32 v34, v150, v151
	v_cvt_pk_bf16_f32 v35, v152, v153
	v_cvt_pk_bf16_f32 v36, v154, v155
	v_cvt_pk_bf16_f32 v37, v156, v157
	v_cvt_pk_bf16_f32 v38, v158, v159
	v_cvt_pk_bf16_f32 v39, v160, v161
	v_xor_b32_e32 v198, 16, v249
	v_xor_b32_e32 v199, 32, v249
	v_xor_b32_e32 v200, 48, v249
	ds_write_b64 v249, v[32:33] offset:8192
	ds_write_b64 v198, v[34:35] offset:8192
	ds_write_b64 v199, v[36:37] offset:8192
	ds_write_b64 v200, v[38:39] offset:8192
	s_branch .Lgs1_next
.Lgs1_otail:
	s_cmp_eq_u32 s16, 0
	s_cbranch_scc1 .Lgs1_next
	s_add_i32 s65, s54, -1
	s_add_i32 s1, s65, -4
	s_cmp_lt_u32 s65, 4
	s_cselect_b32 s0, s65, s1
	s_movk_i32 s5, 0x1000
	s_cselect_b32 s1, 0x100, s5
	s_lshl_b32 s4, s35, 8
	s_add_u32 s4, s4, 0x8000
	s_lshl_b32 s5, s35, 12
	s_cmp_lt_u32 s65, 4
	s_cselect_b32 s4, s4, s5
	s_lshl_b32 s0, s0, 6
	s_sub_u32 s1, s1, 64
	s_sub_u32 s1, s1, s0
	s_cmp_eq_u32 s55, 0
	s_cselect_b32 s0, s0, s1
	s_add_u32 s0, s4, s0
	s_lshl_b32 s1, s0, 11
	s_add_u32 s20, s30, s1
	s_addc_u32 s21, s31, 0
	v_cvt_pk_bf16_f32 v186, v16, v17
	v_cvt_pk_bf16_f32 v187, v18, v19
	v_cvt_pk_bf16_f32 v188, v20, v21
	v_cvt_pk_bf16_f32 v189, v22, v23
	v_cvt_pk_bf16_f32 v190, v24, v25
	v_cvt_pk_bf16_f32 v191, v26, v27
	v_cvt_pk_bf16_f32 v192, v28, v29
	v_cvt_pk_bf16_f32 v193, v30, v31
	s_nop 0
	v_permlane32_swap_b32_e32 v186, v188
	v_permlane32_swap_b32_e32 v187, v189
	v_permlane32_swap_b32_e32 v190, v192
	v_permlane32_swap_b32_e32 v191, v193
	global_store_dwordx4 v204, v[186:189], s[20:21]
	global_store_dwordx4 v204, v[190:193], s[20:21] offset:32
	s_mov_b32 s97, 2

; __device__ __forceinline__ void gla_scan_phase(const Params& p, int j, bool need_ctx, char* smem, int tid, int bid) {
;     ...
;       if (!need_o) {
;       } else if (wid < 4) {
;         const int sb = wid & 1, tb = wid >> 1;
;         if (sb <= tb) {
;           f32x16 sacc;
; #pragma unroll
;           for (int r = 0; r < 16; ++r) sacc[r] = 0.f;
;           bf16x8 av[8], bv8[8];
; #pragma unroll
;           for (int k16 = 0; k16 < 8; ++k16) {
;             av[k16] = *(const bf16x8*)(kinvL + swz256(sb * 32 + l32, k16 * 2 + hi));
;             bv8[k16] = *(const bf16x8*)(qbL + swz256(tb * 32 + l32, k16 * 2 + hi));
;           }
; #pragma unroll
;           for (int k16 = 0; k16 < 8; ++k16) sacc = __builtin_amdgcn_mfma_f32_32x32x16_bf16(av[k16], bv8[k16], sacc, 0, 0, 0);
;           const int t = tb * 32 + l32;
; #pragma unroll
;           for (int rg = 0; rg < 4; ++rg) {
;             const int s0 = sb * 32 + 8 * rg + 4 * hi;
;             const float v0 = (s0 + 0 <= t) ? sacc[rg * 4 + 0] : 0.f, v1 = (s0 + 1 <= t) ? sacc[rg * 4 + 1] : 0.f;
;             const float v2 = (s0 + 2 <= t) ? sacc[rg * 4 + 2] : 0.f, v3 = (s0 + 3 <= t) ? sacc[rg * 4 + 3] : 0.f;
;             u32x2 w = {cvtpk(v0, v1), cvtpk(v2, v3)};
;             *(u32x2*)(scL + swz128(t, s0 >> 3) + (s0 & 7) * 2) = w;
;           }
;         }
;       } else {
;         bf16x8 av[8], bv8[8];
; #pragma unroll
;         for (int k16 = 0; k16 < 8; ++k16) {
;           av[k16] = *(const bf16x8*)(qbL + swz256(tbo * 32 + l32, k16 * 2 + hi));
;           bv8[k16] = *(const bf16x8*)(STL + swz256(dvbo * 32 + l32, k16 * 2 + hi));
;         }
; #pragma unroll
;         for (int k16 = 0; k16 < 8; ++k16) oacc = __builtin_amdgcn_mfma_f32_32x32x16_bf16(av[k16], bv8[k16], oacc, 0, 0, 0);
;       }
;       const int kb = wid >> 1, dvb2 = wid & 1;
;       {
;         bf16x8 av[4], bv4[4];
; #pragma unroll
;         for (int k16 = 0; k16 < 4; ++k16) {
;           av[k16] = *(const bf16x8*)(kendT + swz128(kb * 32 + l32, k16 * 2 + hi));
;           bv4[k16] = *(const bf16x8*)(vT + swz128(dvb2 * 32 + l32, k16 * 2 + hi));
;         }
; #pragma unroll
;         for (int k16 = 0; k16 < 4; ++k16) Sacc = __builtin_amdgcn_mfma_f32_32x32x16_bf16(av[k16], bv4[k16], Sacc, 0, 0, 0);
; #pragma unroll
;         for (int rg = 0; rg < 4; ++rg) {
;           const f32x4 e4 = *(const f32x4*)(ebend + kb * 32 + 8 * rg + 4 * hi);
.Lgs2_chunk:
	s_cmp_gt_u32 s54, 3
	s_cselect_b32 s96, 1, s60
	s_waitcnt lgkmcnt(0)
	s_barrier
	s_cmp_eq_u32 s54, 68
	s_cbranch_scc1 .Lgs_tail
	ds_read_b64_tr_b16 v[64:65], v140 offset:0
	ds_read_b64_tr_b16 v[66:67], v141 offset:0
	ds_read_b64_tr_b16 v[80:81], v142 offset:0
	ds_read_b64_tr_b16 v[82:83], v142 offset:512
	ds_read_b64_tr_b16 v[68:69], v140 offset:4096
	ds_read_b64_tr_b16 v[70:71], v141 offset:4096
	ds_read_b64_tr_b16 v[84:85], v142 offset:2048
	ds_read_b64_tr_b16 v[86:87], v142 offset:2560
	ds_read_b64_tr_b16 v[72:73], v140 offset:8192
	ds_read_b64_tr_b16 v[74:75], v141 offset:8192
	ds_read_b64_tr_b16 v[88:89], v142 offset:4096
	ds_read_b64_tr_b16 v[90:91], v142 offset:4608
	s_add_u32 s65, s54, 3
	s_min_u32 s65, s65, 67
	s_add_i32 s1, s65, -4
	s_cmp_lt_u32 s65, 4
	s_cselect_b32 s0, s65, s1
	s_movk_i32 s5, 0x1000
	s_cselect_b32 s1, 0x100, s5
	s_lshl_b32 s4, s35, 8
	s_add_u32 s4, s4, 0x8000
	s_lshl_b32 s5, s35, 12
	s_cmp_lt_u32 s65, 4
	s_cselect_b32 s4, s4, s5
	s_lshl_b32 s0, s0, 6
	s_sub_u32 s1, s1, 64
	s_sub_u32 s1, s1, s0
	s_cmp_eq_u32 s55, 0
	s_cselect_b32 s0, s0, s1
	s_add_u32 s0, s4, s0
	s_mul_i32 s1, s0, s34
	s_add_u32 s6, s22, s1
	s_addc_u32 s7, s23, 0
	s_add_u32 s8, s24, s1
	s_addc_u32 s9, s25, 0
	s_mul_i32 s1, s0, 0x1840
	s_add_u32 s10, s26, s1
	s_addc_u32 s11, s27, 0
	s_lshr_b32 s1, s0, 6
	s_lshl_b32 s1, s1, 11
	s_add_u32 s18, s28, s1
	s_addc_u32 s19, s29, 0
	s_waitcnt lgkmcnt(8)
	v_mfma_f32_32x32x16_bf16 v[0:15], v[64:67], v[80:83], v[0:15]
	ds_read_b64_tr_b16 v[76:77], v140 offset:12288
	ds_read_b64_tr_b16 v[78:79], v141 offset:12288
	ds_read_b64_tr_b16 v[92:93], v142 offset:6144
	ds_read_b64_tr_b16 v[94:95], v142 offset:6656
	s_cmp_eq_u32 s96, 0
	s_cbranch_scc1 .Lgs2_nochain
	s_cmp_eq_u32 s76, 1
	s_cbranch_scc1 .Lgs2_nochain
	s_waitcnt lgkmcnt(8)
	v_mfma_f32_32x32x16_bf16 v[0:15], v[68:71], v[84:87], v[0:15]
	ds_read_b128 v[32:35], v243
	ds_read_b128 v[48:51], v221 offset:0
	v_xor_b32_e32 v198, 32, v243
	v_xor_b32_e32 v199, 32, v221
	ds_read_b128 v[36:39], v198
	ds_read_b128 v[52:55], v199 offset:0
	global_load_dwordx4 v[222:225], v134, s[6:7]
	s_waitcnt lgkmcnt(8)
	v_mfma_f32_32x32x16_bf16 v[0:15], v[72:75], v[88:91], v[0:15]
	v_xor_b32_e32 v198, 64, v243
	v_xor_b32_e32 v199, 64, v221
	ds_read_b128 v[40:43], v198
	ds_read_b128 v[56:59], v199 offset:0
	v_xor_b32_e32 v198, 96, v243
	v_xor_b32_e32 v199, 96, v221
	ds_read_b128 v[44:47], v198
	ds_read_b128 v[60:63], v199 offset:0
	global_load_dwordx4 v[226:229], v134, s[6:7] offset:128
	s_waitcnt lgkmcnt(8)
	v_mfma_f32_32x32x16_bf16 v[0:15], v[76:79], v[92:95], v[0:15]
	global_load_dwordx4 v[230:233], v134, s[8:9]
	s_waitcnt lgkmcnt(6)
	v_mfma_f32_32x32x16_bf16 v[16:31], v[32:35], v[48:51], 0
	v_xor_b32_e32 v198, 128, v243
	v_xor_b32_e32 v199, 128, v221
	ds_read_b128 v[32:35], v198
	ds_read_b128 v[48:51], v199 offset:0
	global_load_dwordx4 v[234:237], v134, s[8:9] offset:128
	s_waitcnt lgkmcnt(6)
	v_mfma_f32_32x32x16_bf16 v[16:31], v[36:39], v[52:55], v[16:31]
	v_xor_b32_e32 v198, 160, v243
	v_xor_b32_e32 v199, 160, v221
	ds_read_b128 v[36:39], v198
	ds_read_b128 v[52:55], v199 offset:0
	global_load_dwordx4 v[244:247], v135, s[10:11]
	s_waitcnt lgkmcnt(6)
	v_mfma_f32_32x32x16_bf16 v[16:31], v[40:43], v[56:59], v[16:31]
	v_xor_b32_e32 v198, 192, v243
	v_xor_b32_e32 v199, 192, v221
	ds_read_b128 v[40:43], v198
	ds_read_b128 v[56:59], v199 offset:0
	global_load_dword v248, v145, s[18:19]
	s_waitcnt lgkmcnt(6)
	v_mfma_f32_32x32x16_bf16 v[16:31], v[44:47], v[60:63], v[16:31]
	v_xor_b32_e32 v198, 224, v243
	v_xor_b32_e32 v199, 224, v221
	ds_read_b128 v[44:47], v198
	ds_read_b128 v[60:63], v199 offset:0
	s_waitcnt lgkmcnt(6)
	v_mfma_f32_32x32x16_bf16 v[16:31], v[32:35], v[48:51], v[16:31]
	ds_read_b128 v[178:181], v252 offset:0
	ds_read_b128 v[182:185], v252 offset:32
	ds_read_b128 v[186:189], v252 offset:64
	ds_read_b128 v[190:193], v252 offset:96
	s_waitcnt lgkmcnt(8)
	v_mfma_f32_32x32x16_bf16 v[16:31], v[36:39], v[52:55], v[16:31]
	s_waitcnt lgkmcnt(6)
	v_mfma_f32_32x32x16_bf16 v[16:31], v[40:43], v[56:59], v[16:31]
	s_waitcnt lgkmcnt(4)
	v_mfma_f32_32x32x16_bf16 v[16:31], v[44:47], v[60:63], v[16:31]
	s_cmp_eq_u32 s16, 0
	s_cbranch_scc1 .Lgs2_scale
	s_cmp_eq_u32 s76, 2
	s_cbranch_scc0 .Lgs2_scale
	v_xor_b32_e32 v198, 32, v249
	ds_read_b128 v[64:67], v249 offset:8192
	ds_read_b128 v[68:71], v198 offset:8192
	s_cmp_eq_u32 s77, 0
	s_cbranch_scc1 .Lgs2_ohalf
	v_xor_b32_e32 v199, 64, v249
	v_xor_b32_e32 v200, 96, v249
	ds_read_b128 v[72:75], v199 offset:8192
	ds_read_b128 v[76:79], v200 offset:8192
	s_waitcnt lgkmcnt(2)
	v_mfma_f32_32x32x16_bf16 v[146:161], v[162:165], v[64:67], v[146:161]
	v_mfma_f32_32x32x16_bf16 v[146:161], v[166:169], v[68:71], v[146:161]
	s_waitcnt lgkmcnt(0)
	v_mfma_f32_32x32x16_bf16 v[146:161], v[170:173], v[72:75], v[146:161]
	v_mfma_f32_32x32x16_bf16 v[146:161], v[174:177], v[76:79], v[146:161]
	s_branch .Lgs2_odone

; __device__ __forceinline__ void gla_scan_phase(const Params& p, int j, bool need_ctx, char* smem, int tid, int bid) {
;     ...
;       const int kb = wid >> 1, dvb2 = wid & 1;
;       {
;         bf16x8 av[4], bv4[4];
; #pragma unroll
;         for (int k16 = 0; k16 < 4; ++k16) {
;           av[k16] = *(const bf16x8*)(kendT + swz128(kb * 32 + l32, k16 * 2 + hi));
;           bv4[k16] = *(const bf16x8*)(vT + swz128(dvb2 * 32 + l32, k16 * 2 + hi));
;         }
; #pragma unroll
;         for (int k16 = 0; k16 < 4; ++k16) Sacc = __builtin_amdgcn_mfma_f32_32x32x16_bf16(av[k16], bv4[k16], Sacc, 0, 0, 0);
; #pragma unroll
;         for (int rg = 0; rg < 4; ++rg) {
;           const f32x4 e4 = *(const f32x4*)(ebend + kb * 32 + 8 * rg + 4 * hi);
;           Sacc[rg * 4 + 0] *= e4[0]; Sacc[rg * 4 + 1] *= e4[1]; Sacc[rg * 4 + 2] *= e4[2]; Sacc[rg * 4 + 3] *= e4[3];
;         }
;       }
.Lgs2_nochain:
	s_waitcnt lgkmcnt(8)
	v_mfma_f32_32x32x16_bf16 v[0:15], v[68:71], v[84:87], v[0:15]
	ds_read_b128 v[178:181], v252 offset:0
	ds_read_b128 v[182:185], v252 offset:32
	ds_read_b128 v[186:189], v252 offset:64
	ds_read_b128 v[190:193], v252 offset:96
	global_load_dwordx4 v[222:225], v134, s[6:7]
	global_load_dwordx4 v[226:229], v134, s[6:7] offset:128
	global_load_dwordx4 v[230:233], v134, s[8:9]
	global_load_dwordx4 v[234:237], v134, s[8:9] offset:128
	global_load_dwordx4 v[244:247], v135, s[10:11]
	global_load_dword v248, v145, s[18:19]
	s_waitcnt lgkmcnt(8)
	v_mfma_f32_32x32x16_bf16 v[0:15], v[72:75], v[88:91], v[0:15]
	s_waitcnt lgkmcnt(4)
	v_mfma_f32_32x32x16_bf16 v[0:15], v[76:79], v[92:95], v[0:15]
	s_nop 7
	s_nop 7

; __device__ __forceinline__ void gla_scan_phase(const Params& p, int j, bool need_ctx, char* smem, int tid, int bid) {
;     ...
;       {
;         if (tid < 128) ebend[tid] = ebv;
;         const int r = tid >> 3, c0 = tid & 7;
;         *(u32x4*)(qbL + swz256(r, c0)) = qx[0]; *(u32x4*)(qbL + swz256(r, c0 + 8)) = qx[1];
;         *(u32x4*)(kinvL + swz256(r, c0)) = kx[0]; *(u32x4*)(kinvL + swz256(r, c0 + 8)) = kx[1];
;         const int kdt = tid & 127, tgk = tid >> 7;
;         u32x4 w0 = {kt[0] | (kt[1] << 16), kt[2] | (kt[3] << 16), kt[4] | (kt[5] << 16), kt[6] | (kt[7] << 16)};
;         u32x4 w1 = {kt[8] | (kt[9] << 16), kt[10] | (kt[11] << 16), kt[12] | (kt[13] << 16), kt[14] | (kt[15] << 16)};
;         *(u32x4*)(kendT + swz128(kdt, tgk)) = w0;
;         *(u32x4*)(kendT + swz128(kdt, tgk + 4)) = w1;
;         u32x4 wv = {vv[0] | (vv[1] << 16), vv[2] | (vv[3] << 16), vv[4] | (vv[5] << 16), vv[6] | (vv[7] << 16)};
;         *(u32x4*)(vT + swz128(dvc, tg)) = wv;
;       }
.Lgs2_wd:
	ds_write_b128 v194, v[112:115] offset:40960
	ds_write_b128 v195, v[116:119] offset:40960
	ds_write_b128 v143, v[120:123] offset:57344
	ds_write_b128 v144, v[124:127] offset:57344
	ds_write_b128 v196, v[128:131] offset:40960
	s_cmp_gt_u32 s81, 1
	s_cbranch_scc1 .Lgs_noeb_b2
	ds_write_b32 v197, v132 offset:512

; __device__ __forceinline__ void gla_scan_phase(const Params& p, int j, bool need_ctx, char* smem, int tid, int bid) {
;     ...
;       if (!need_o) {
;       } else if (wid < 4) {
;         const int sb = wid & 1, tb = wid >> 1;
;         if (sb <= tb) {
;           f32x16 sacc;
; #pragma unroll
;           for (int r = 0; r < 16; ++r) sacc[r] = 0.f;
;           bf16x8 av[8], bv8[8];
; #pragma unroll
;           for (int k16 = 0; k16 < 8; ++k16) {
;             av[k16] = *(const bf16x8*)(kinvL + swz256(sb * 32 + l32, k16 * 2 + hi));
;             bv8[k16] = *(const bf16x8*)(qbL + swz256(tb * 32 + l32, k16 * 2 + hi));
;           }
; #pragma unroll
;           for (int k16 = 0; k16 < 8; ++k16) sacc = __builtin_amdgcn_mfma_f32_32x32x16_bf16(av[k16], bv8[k16], sacc, 0, 0, 0);
;           const int t = tb * 32 + l32;
; #pragma unroll
;           for (int rg = 0; rg < 4; ++rg) {
;             const int s0 = sb * 32 + 8 * rg + 4 * hi;
;             const float v0 = (s0 + 0 <= t) ? sacc[rg * 4 + 0] : 0.f, v1 = (s0 + 1 <= t) ? sacc[rg * 4 + 1] : 0.f;
;             const float v2 = (s0 + 2 <= t) ? sacc[rg * 4 + 2] : 0.f, v3 = (s0 + 3 <= t) ? sacc[rg * 4 + 3] : 0.f;
;             u32x2 w = {cvtpk(v0, v1), cvtpk(v2, v3)};
;             *(u32x2*)(scL + swz128(t, s0 >> 3) + (s0 & 7) * 2) = w;
;           }
;         }
;       } else {
;         bf16x8 av[8], bv8[8];
; #pragma unroll
;         for (int k16 = 0; k16 < 8; ++k16) {
;           av[k16] = *(const bf16x8*)(qbL + swz256(tbo * 32 + l32, k16 * 2 + hi));
;           bv8[k16] = *(const bf16x8*)(STL + swz256(dvbo * 32 + l32, k16 * 2 + hi));
;         }
; #pragma unroll
;         for (int k16 = 0; k16 < 8; ++k16) oacc = __builtin_amdgcn_mfma_f32_32x32x16_bf16(av[k16], bv8[k16], oacc, 0, 0, 0);
;       }
;       const int kb = wid >> 1, dvb2 = wid & 1;
;       {
;         bf16x8 av[4], bv4[4];
; #pragma unroll
;         for (int k16 = 0; k16 < 4; ++k16) {
;           av[k16] = *(const bf16x8*)(kendT + swz128(kb * 32 + l32, k16 * 2 + hi));
;           bv4[k16] = *(const bf16x8*)(vT + swz128(dvb2 * 32 + l32, k16 * 2 + hi));
;         }
; #pragma unroll
;         for (int k16 = 0; k16 < 4; ++k16) Sacc = __builtin_amdgcn_mfma_f32_32x32x16_bf16(av[k16], bv4[k16], Sacc, 0, 0, 0);
; #pragma unroll
;         for (int rg = 0; rg < 4; ++rg) {
;           const f32x4 e4 = *(const f32x4*)(ebend + kb * 32 + 8 * rg + 4 * hi);
.Lgs3_chunk:
	s_cmp_gt_u32 s54, 3
	s_cselect_b32 s96, 1, s60
	s_waitcnt lgkmcnt(0)
	s_barrier
	ds_read_b64_tr_b16 v[64:65], v140 offset:40960
	ds_read_b64_tr_b16 v[66:67], v141 offset:40960
	ds_read_b64_tr_b16 v[162:163], v142 offset:40960
	ds_read_b64_tr_b16 v[164:165], v142 offset:41472
	ds_read_b64_tr_b16 v[68:69], v140 offset:45056
	ds_read_b64_tr_b16 v[70:71], v141 offset:45056
	ds_read_b64_tr_b16 v[166:167], v142 offset:43008
	ds_read_b64_tr_b16 v[168:169], v142 offset:43520
	ds_read_b64_tr_b16 v[72:73], v140 offset:49152
	ds_read_b64_tr_b16 v[74:75], v141 offset:49152
	ds_read_b64_tr_b16 v[170:171], v142 offset:45056
	ds_read_b64_tr_b16 v[172:173], v142 offset:45568
	s_add_u32 s65, s54, 3
	s_min_u32 s65, s65, 67
	s_add_i32 s1, s65, -4
	s_cmp_lt_u32 s65, 4
	s_cselect_b32 s0, s65, s1
	s_movk_i32 s5, 0x1000
	s_cselect_b32 s1, 0x100, s5
	s_lshl_b32 s4, s35, 8
	s_add_u32 s4, s4, 0x8000
	s_lshl_b32 s5, s35, 12
	s_cmp_lt_u32 s65, 4
	s_cselect_b32 s4, s4, s5
	s_lshl_b32 s0, s0, 6
	s_sub_u32 s1, s1, 64
	s_sub_u32 s1, s1, s0
	s_cmp_eq_u32 s55, 0
	s_cselect_b32 s0, s0, s1
	s_add_u32 s0, s4, s0
	s_mul_i32 s1, s0, s34
	s_add_u32 s6, s22, s1
	s_addc_u32 s7, s23, 0
	s_add_u32 s8, s24, s1
	s_addc_u32 s9, s25, 0
	s_mul_i32 s1, s0, 0x1840
	s_add_u32 s10, s26, s1
	s_addc_u32 s11, s27, 0
	s_lshr_b32 s1, s0, 6
	s_lshl_b32 s1, s1, 11
	s_add_u32 s18, s28, s1
	s_addc_u32 s19, s29, 0
	s_waitcnt lgkmcnt(8)
	v_mfma_f32_32x32x16_bf16 v[0:15], v[64:67], v[162:165], v[0:15]
	ds_read_b64_tr_b16 v[76:77], v140 offset:53248
	ds_read_b64_tr_b16 v[78:79], v141 offset:53248
	ds_read_b64_tr_b16 v[174:175], v142 offset:47104
	ds_read_b64_tr_b16 v[176:177], v142 offset:47616
	s_cmp_eq_u32 s96, 0
	s_cbranch_scc1 .Lgs3_nochain
	s_cmp_eq_u32 s76, 1
	s_cbranch_scc1 .Lgs3_nochain
	s_waitcnt lgkmcnt(8)
	v_mfma_f32_32x32x16_bf16 v[0:15], v[68:71], v[166:169], v[0:15]
	ds_read_b128 v[32:35], v220
	ds_read_b128 v[48:51], v221 offset:40960
	v_xor_b32_e32 v198, 32, v220
	v_xor_b32_e32 v199, 32, v221
	ds_read_b128 v[36:39], v198
	ds_read_b128 v[52:55], v199 offset:40960
	global_load_dwordx4 v[112:115], v134, s[6:7]
	s_waitcnt lgkmcnt(8)
	v_mfma_f32_32x32x16_bf16 v[0:15], v[72:75], v[170:173], v[0:15]
	v_xor_b32_e32 v198, 64, v220
	v_xor_b32_e32 v199, 64, v221
	ds_read_b128 v[40:43], v198
	ds_read_b128 v[56:59], v199 offset:40960
	v_xor_b32_e32 v198, 96, v220
	v_xor_b32_e32 v199, 96, v221
	ds_read_b128 v[44:47], v198
	ds_read_b128 v[60:63], v199 offset:40960
	global_load_dwordx4 v[116:119], v134, s[6:7] offset:128
	s_waitcnt lgkmcnt(8)
	v_mfma_f32_32x32x16_bf16 v[0:15], v[76:79], v[174:177], v[0:15]
	global_load_dwordx4 v[120:123], v134, s[8:9]
	s_waitcnt lgkmcnt(6)
	v_mfma_f32_32x32x16_bf16 v[146:161], v[32:35], v[48:51], 0
	v_xor_b32_e32 v198, 128, v220
	v_xor_b32_e32 v199, 128, v221
	ds_read_b128 v[32:35], v198
	ds_read_b128 v[48:51], v199 offset:40960
	global_load_dwordx4 v[124:127], v134, s[8:9] offset:128
	s_waitcnt lgkmcnt(6)
	v_mfma_f32_32x32x16_bf16 v[146:161], v[36:39], v[52:55], v[146:161]
	v_xor_b32_e32 v198, 160, v220
	v_xor_b32_e32 v199, 160, v221
	ds_read_b128 v[36:39], v198
	ds_read_b128 v[52:55], v199 offset:40960
	global_load_dwordx4 v[128:131], v135, s[10:11]
	s_waitcnt lgkmcnt(6)
	v_mfma_f32_32x32x16_bf16 v[146:161], v[40:43], v[56:59], v[146:161]
	v_xor_b32_e32 v198, 192, v220
	v_xor_b32_e32 v199, 192, v221
	ds_read_b128 v[40:43], v198
	ds_read_b128 v[56:59], v199 offset:40960
	global_load_dword v132, v145, s[18:19]
	s_waitcnt lgkmcnt(6)
	v_mfma_f32_32x32x16_bf16 v[146:161], v[44:47], v[60:63], v[146:161]
	v_xor_b32_e32 v198, 224, v220
	v_xor_b32_e32 v199, 224, v221
	ds_read_b128 v[44:47], v198
	ds_read_b128 v[60:63], v199 offset:40960
	s_waitcnt lgkmcnt(6)
	v_mfma_f32_32x32x16_bf16 v[146:161], v[32:35], v[48:51], v[146:161]
	ds_read_b128 v[178:181], v252 offset:512
	ds_read_b128 v[182:185], v252 offset:544
	ds_read_b128 v[186:189], v252 offset:576
	ds_read_b128 v[190:193], v252 offset:608
	s_waitcnt lgkmcnt(8)
	v_mfma_f32_32x32x16_bf16 v[146:161], v[36:39], v[52:55], v[146:161]
	s_waitcnt lgkmcnt(6)
	v_mfma_f32_32x32x16_bf16 v[146:161], v[40:43], v[56:59], v[146:161]
	s_waitcnt lgkmcnt(4)
	v_mfma_f32_32x32x16_bf16 v[146:161], v[44:47], v[60:63], v[146:161]
	s_cmp_eq_u32 s16, 0
	s_cbranch_scc1 .Lgs3_scale
	s_cmp_eq_u32 s76, 2
	s_cbranch_scc0 .Lgs3_scale
	v_xor_b32_e32 v198, 32, v249
	ds_read_b128 v[64:67], v249 offset:0
	ds_read_b128 v[68:71], v198 offset:0
	s_cmp_eq_u32 s77, 0
	s_cbranch_scc1 .Lgs3_ohalf
	v_xor_b32_e32 v199, 64, v249
	v_xor_b32_e32 v200, 96, v249
	ds_read_b128 v[72:75], v199 offset:0
	ds_read_b128 v[76:79], v200 offset:0
	s_waitcnt lgkmcnt(2)
	v_mfma_f32_32x32x16_bf16 v[16:31], v[80:83], v[64:67], v[16:31]
	v_mfma_f32_32x32x16_bf16 v[16:31], v[84:87], v[68:71], v[16:31]
	s_waitcnt lgkmcnt(0)
	v_mfma_f32_32x32x16_bf16 v[16:31], v[88:91], v[72:75], v[16:31]
	v_mfma_f32_32x32x16_bf16 v[16:31], v[92:95], v[76:79], v[16:31]
	s_branch .Lgs3_odone

; __device__ __forceinline__ void gla_scan_phase(const Params& p, int j, bool need_ctx, char* smem, int tid, int bid) {
;     ...
;       const int kb = wid >> 1, dvb2 = wid & 1;
;       {
;         bf16x8 av[4], bv4[4];
; #pragma unroll
;         for (int k16 = 0; k16 < 4; ++k16) {
;           av[k16] = *(const bf16x8*)(kendT + swz128(kb * 32 + l32, k16 * 2 + hi));
;           bv4[k16] = *(const bf16x8*)(vT + swz128(dvb2 * 32 + l32, k16 * 2 + hi));
;         }
; #pragma unroll
;         for (int k16 = 0; k16 < 4; ++k16) Sacc = __builtin_amdgcn_mfma_f32_32x32x16_bf16(av[k16], bv4[k16], Sacc, 0, 0, 0);
; #pragma unroll
;         for (int rg = 0; rg < 4; ++rg) {
;           const f32x4 e4 = *(const f32x4*)(ebend + kb * 32 + 8 * rg + 4 * hi);
;           Sacc[rg * 4 + 0] *= e4[0]; Sacc[rg * 4 + 1] *= e4[1]; Sacc[rg * 4 + 2] *= e4[2]; Sacc[rg * 4 + 3] *= e4[3];
;         }
;       }
.Lgs3_nochain:
	s_waitcnt lgkmcnt(8)
	v_mfma_f32_32x32x16_bf16 v[0:15], v[68:71], v[166:169], v[0:15]
	ds_read_b128 v[178:181], v252 offset:512
	ds_read_b128 v[182:185], v252 offset:544
	ds_read_b128 v[186:189], v252 offset:576
	ds_read_b128 v[190:193], v252 offset:608
	global_load_dwordx4 v[112:115], v134, s[6:7]
	global_load_dwordx4 v[116:119], v134, s[6:7] offset:128
	global_load_dwordx4 v[120:123], v134, s[8:9]
	global_load_dwordx4 v[124:127], v134, s[8:9] offset:128
	global_load_dwordx4 v[128:131], v135, s[10:11]
	global_load_dword v132, v145, s[18:19]
	s_waitcnt lgkmcnt(8)
	v_mfma_f32_32x32x16_bf16 v[0:15], v[72:75], v[170:173], v[0:15]
	s_waitcnt lgkmcnt(4)
	v_mfma_f32_32x32x16_bf16 v[0:15], v[76:79], v[174:177], v[0:15]
	s_nop 7
	s_nop 7

; __device__ __forceinline__ void gla_scan_phase(const Params& p, int j, bool need_ctx, char* smem, int tid, int bid) {
;     ...
;       {
;         if (tid < 128) ebend[tid] = ebv;
;         const int r = tid >> 3, c0 = tid & 7;
;         *(u32x4*)(qbL + swz256(r, c0)) = qx[0]; *(u32x4*)(qbL + swz256(r, c0 + 8)) = qx[1];
;         *(u32x4*)(kinvL + swz256(r, c0)) = kx[0]; *(u32x4*)(kinvL + swz256(r, c0 + 8)) = kx[1];
;         const int kdt = tid & 127, tgk = tid >> 7;
;         u32x4 w0 = {kt[0] | (kt[1] << 16), kt[2] | (kt[3] << 16), kt[4] | (kt[5] << 16), kt[6] | (kt[7] << 16)};
;         u32x4 w1 = {kt[8] | (kt[9] << 16), kt[10] | (kt[11] << 16), kt[12] | (kt[13] << 16), kt[14] | (kt[15] << 16)};
;         *(u32x4*)(kendT + swz128(kdt, tgk)) = w0;
;         *(u32x4*)(kendT + swz128(kdt, tgk + 4)) = w1;
;         u32x4 wv = {vv[0] | (vv[1] << 16), vv[2] | (vv[3] << 16), vv[4] | (vv[5] << 16), vv[6] | (vv[7] << 16)};
;         *(u32x4*)(vT + swz128(dvc, tg)) = wv;
;       }
.Lgs3_wd:
	ds_write_b128 v194, v[96:99] offset:0
	ds_write_b128 v195, v[100:103] offset:0
	ds_write_b128 v143, v[104:107] offset:16384
	ds_write_b128 v144, v[108:111] offset:16384
	ds_write_b128 v196, v[136:139] offset:0
	s_cmp_gt_u32 s81, 1
	s_cbranch_scc1 .Lgs_noeb_b3
	ds_write_b32 v197, v133 offset:0

; __device__ __forceinline__ void gla_scan_phase(const Params& p, int j, bool need_ctx, char* smem, int tid, int bid) {
;     ...
;       if (!need_o) {
;       } else if (wid < 4) {
;         const int sb = wid & 1, tb = wid >> 1;
;         if (sb <= tb) {
;           f32x16 sacc;
; #pragma unroll
;           for (int r = 0; r < 16; ++r) sacc[r] = 0.f;
;           bf16x8 av[8], bv8[8];
; #pragma unroll
;           for (int k16 = 0; k16 < 8; ++k16) {
;             av[k16] = *(const bf16x8*)(kinvL + swz256(sb * 32 + l32, k16 * 2 + hi));
;             bv8[k16] = *(const bf16x8*)(qbL + swz256(tb * 32 + l32, k16 * 2 + hi));
;           }
; #pragma unroll
;           for (int k16 = 0; k16 < 8; ++k16) sacc = __builtin_amdgcn_mfma_f32_32x32x16_bf16(av[k16], bv8[k16], sacc, 0, 0, 0);
;           const int t = tb * 32 + l32;
; #pragma unroll
;           for (int rg = 0; rg < 4; ++rg) {
;             const int s0 = sb * 32 + 8 * rg + 4 * hi;
;             const float v0 = (s0 + 0 <= t) ? sacc[rg * 4 + 0] : 0.f, v1 = (s0 + 1 <= t) ? sacc[rg * 4 + 1] : 0.f;
;             const float v2 = (s0 + 2 <= t) ? sacc[rg * 4 + 2] : 0.f, v3 = (s0 + 3 <= t) ? sacc[rg * 4 + 3] : 0.f;
;             u32x2 w = {cvtpk(v0, v1), cvtpk(v2, v3)};
;             *(u32x2*)(scL + swz128(t, s0 >> 3) + (s0 & 7) * 2) = w;
;           }
;         }
;       } else {
;         bf16x8 av[8], bv8[8];
; #pragma unroll
;         for (int k16 = 0; k16 < 8; ++k16) {
;           av[k16] = *(const bf16x8*)(qbL + swz256(tbo * 32 + l32, k16 * 2 + hi));
;           bv8[k16] = *(const bf16x8*)(STL + swz256(dvbo * 32 + l32, k16 * 2 + hi));
;         }
; #pragma unroll
;         for (int k16 = 0; k16 < 8; ++k16) oacc = __builtin_amdgcn_mfma_f32_32x32x16_bf16(av[k16], bv8[k16], oacc, 0, 0, 0);
;       }
;       const int kb = wid >> 1, dvb2 = wid & 1;
;       {
;         bf16x8 av[4], bv4[4];
; #pragma unroll
;         for (int k16 = 0; k16 < 4; ++k16) {
;           av[k16] = *(const bf16x8*)(kendT + swz128(kb * 32 + l32, k16 * 2 + hi));
;           bv4[k16] = *(const bf16x8*)(vT + swz128(dvb2 * 32 + l32, k16 * 2 + hi));
;         }
; #pragma unroll
;         for (int k16 = 0; k16 < 4; ++k16) Sacc = __builtin_amdgcn_mfma_f32_32x32x16_bf16(av[k16], bv4[k16], Sacc, 0, 0, 0);
; #pragma unroll
;         for (int rg = 0; rg < 4; ++rg) {
;           const f32x4 e4 = *(const f32x4*)(ebend + kb * 32 + 8 * rg + 4 * hi);
.Lgs4_chunk:
	s_cmp_gt_u32 s54, 3
	s_cselect_b32 s96, 1, s60
	s_waitcnt lgkmcnt(0)
	s_barrier
	ds_read_b64_tr_b16 v[64:65], v140 offset:0
	ds_read_b64_tr_b16 v[66:67], v141 offset:0
	ds_read_b64_tr_b16 v[80:81], v142 offset:0
	ds_read_b64_tr_b16 v[82:83], v142 offset:512
	ds_read_b64_tr_b16 v[68:69], v140 offset:4096
	ds_read_b64_tr_b16 v[70:71], v141 offset:4096
	ds_read_b64_tr_b16 v[84:85], v142 offset:2048
	ds_read_b64_tr_b16 v[86:87], v142 offset:2560
	ds_read_b64_tr_b16 v[72:73], v140 offset:8192
	ds_read_b64_tr_b16 v[74:75], v141 offset:8192
	ds_read_b64_tr_b16 v[88:89], v142 offset:4096
	ds_read_b64_tr_b16 v[90:91], v142 offset:4608
	s_add_u32 s65, s54, 3
	s_min_u32 s65, s65, 67
	s_add_i32 s1, s65, -4
	s_cmp_lt_u32 s65, 4
	s_cselect_b32 s0, s65, s1
	s_movk_i32 s5, 0x1000
	s_cselect_b32 s1, 0x100, s5
	s_lshl_b32 s4, s35, 8
	s_add_u32 s4, s4, 0x8000
	s_lshl_b32 s5, s35, 12
	s_cmp_lt_u32 s65, 4
	s_cselect_b32 s4, s4, s5
	s_lshl_b32 s0, s0, 6
	s_sub_u32 s1, s1, 64
	s_sub_u32 s1, s1, s0
	s_cmp_eq_u32 s55, 0
	s_cselect_b32 s0, s0, s1
	s_add_u32 s0, s4, s0
	s_mul_i32 s1, s0, s34
	s_add_u32 s6, s22, s1
	s_addc_u32 s7, s23, 0
	s_add_u32 s8, s24, s1
	s_addc_u32 s9, s25, 0
	s_mul_i32 s1, s0, 0x1840
	s_add_u32 s10, s26, s1
	s_addc_u32 s11, s27, 0
	s_lshr_b32 s1, s0, 6
	s_lshl_b32 s1, s1, 11
	s_add_u32 s18, s28, s1
	s_addc_u32 s19, s29, 0
	s_waitcnt lgkmcnt(8)
	v_mfma_f32_32x32x16_bf16 v[0:15], v[64:67], v[80:83], v[0:15]
	ds_read_b64_tr_b16 v[76:77], v140 offset:12288
	ds_read_b64_tr_b16 v[78:79], v141 offset:12288
	ds_read_b64_tr_b16 v[92:93], v142 offset:6144
	ds_read_b64_tr_b16 v[94:95], v142 offset:6656
	s_cmp_eq_u32 s96, 0
	s_cbranch_scc1 .Lgs4_nochain
	s_cmp_eq_u32 s76, 1
	s_cbranch_scc1 .Lgs4_nochain
	s_waitcnt lgkmcnt(8)
	v_mfma_f32_32x32x16_bf16 v[0:15], v[68:71], v[84:87], v[0:15]
	ds_read_b128 v[32:35], v243
	ds_read_b128 v[48:51], v221 offset:0
	v_xor_b32_e32 v198, 32, v243
	v_xor_b32_e32 v199, 32, v221
	ds_read_b128 v[36:39], v198
	ds_read_b128 v[52:55], v199 offset:0
	global_load_dwordx4 v[96:99], v134, s[6:7]
	s_waitcnt lgkmcnt(8)
	v_mfma_f32_32x32x16_bf16 v[0:15], v[72:75], v[88:91], v[0:15]
	v_xor_b32_e32 v198, 64, v243
	v_xor_b32_e32 v199, 64, v221
	ds_read_b128 v[40:43], v198
	ds_read_b128 v[56:59], v199 offset:0
	v_xor_b32_e32 v198, 96, v243
	v_xor_b32_e32 v199, 96, v221
	ds_read_b128 v[44:47], v198
	ds_read_b128 v[60:63], v199 offset:0
	global_load_dwordx4 v[100:103], v134, s[6:7] offset:128
	s_waitcnt lgkmcnt(8)
	v_mfma_f32_32x32x16_bf16 v[0:15], v[76:79], v[92:95], v[0:15]
	global_load_dwordx4 v[104:107], v134, s[8:9]
	s_waitcnt lgkmcnt(6)
	v_mfma_f32_32x32x16_bf16 v[16:31], v[32:35], v[48:51], 0
	v_xor_b32_e32 v198, 128, v243
	v_xor_b32_e32 v199, 128, v221
	ds_read_b128 v[32:35], v198
	ds_read_b128 v[48:51], v199 offset:0
	global_load_dwordx4 v[108:111], v134, s[8:9] offset:128
	s_waitcnt lgkmcnt(6)
	v_mfma_f32_32x32x16_bf16 v[16:31], v[36:39], v[52:55], v[16:31]
	v_xor_b32_e32 v198, 160, v243
	v_xor_b32_e32 v199, 160, v221
	ds_read_b128 v[36:39], v198
	ds_read_b128 v[52:55], v199 offset:0
	global_load_dwordx4 v[136:139], v135, s[10:11]
	s_waitcnt lgkmcnt(6)
	v_mfma_f32_32x32x16_bf16 v[16:31], v[40:43], v[56:59], v[16:31]
	v_xor_b32_e32 v198, 192, v243
	v_xor_b32_e32 v199, 192, v221
	ds_read_b128 v[40:43], v198
	ds_read_b128 v[56:59], v199 offset:0
	global_load_dword v133, v145, s[18:19]
	s_waitcnt lgkmcnt(6)
	v_mfma_f32_32x32x16_bf16 v[16:31], v[44:47], v[60:63], v[16:31]
	v_xor_b32_e32 v198, 224, v243
	v_xor_b32_e32 v199, 224, v221
	ds_read_b128 v[44:47], v198
	ds_read_b128 v[60:63], v199 offset:0
	s_waitcnt lgkmcnt(6)
	v_mfma_f32_32x32x16_bf16 v[16:31], v[32:35], v[48:51], v[16:31]
	ds_read_b128 v[178:181], v252 offset:0
	ds_read_b128 v[182:185], v252 offset:32
	ds_read_b128 v[186:189], v252 offset:64
	ds_read_b128 v[190:193], v252 offset:96
	s_waitcnt lgkmcnt(8)
	v_mfma_f32_32x32x16_bf16 v[16:31], v[36:39], v[52:55], v[16:31]
	s_waitcnt lgkmcnt(6)
	v_mfma_f32_32x32x16_bf16 v[16:31], v[40:43], v[56:59], v[16:31]
	s_waitcnt lgkmcnt(4)
	v_mfma_f32_32x32x16_bf16 v[16:31], v[44:47], v[60:63], v[16:31]
	s_cmp_eq_u32 s16, 0
	s_cbranch_scc1 .Lgs4_scale
	s_cmp_eq_u32 s76, 2
	s_cbranch_scc0 .Lgs4_scale
	v_xor_b32_e32 v198, 32, v249
	ds_read_b128 v[64:67], v249 offset:8192
	ds_read_b128 v[68:71], v198 offset:8192
	s_cmp_eq_u32 s77, 0
	s_cbranch_scc1 .Lgs4_ohalf
	v_xor_b32_e32 v199, 64, v249
	v_xor_b32_e32 v200, 96, v249
	ds_read_b128 v[72:75], v199 offset:8192
	ds_read_b128 v[76:79], v200 offset:8192
	s_waitcnt lgkmcnt(2)
	v_mfma_f32_32x32x16_bf16 v[146:161], v[162:165], v[64:67], v[146:161]
	v_mfma_f32_32x32x16_bf16 v[146:161], v[166:169], v[68:71], v[146:161]
	s_waitcnt lgkmcnt(0)
	v_mfma_f32_32x32x16_bf16 v[146:161], v[170:173], v[72:75], v[146:161]
	v_mfma_f32_32x32x16_bf16 v[146:161], v[174:177], v[76:79], v[146:161]
	s_branch .Lgs4_odone

; __device__ __forceinline__ void gla_scan_phase(const Params& p, int j, bool need_ctx, char* smem, int tid, int bid) {
;     ...
;       const int kb = wid >> 1, dvb2 = wid & 1;
;       {
;         bf16x8 av[4], bv4[4];
; #pragma unroll
;         for (int k16 = 0; k16 < 4; ++k16) {
;           av[k16] = *(const bf16x8*)(kendT + swz128(kb * 32 + l32, k16 * 2 + hi));
;           bv4[k16] = *(const bf16x8*)(vT + swz128(dvb2 * 32 + l32, k16 * 2 + hi));
;         }
; #pragma unroll
;         for (int k16 = 0; k16 < 4; ++k16) Sacc = __builtin_amdgcn_mfma_f32_32x32x16_bf16(av[k16], bv4[k16], Sacc, 0, 0, 0);
; #pragma unroll
;         for (int rg = 0; rg < 4; ++rg) {
;           const f32x4 e4 = *(const f32x4*)(ebend + kb * 32 + 8 * rg + 4 * hi);
;           Sacc[rg * 4 + 0] *= e4[0]; Sacc[rg * 4 + 1] *= e4[1]; Sacc[rg * 4 + 2] *= e4[2]; Sacc[rg * 4 + 3] *= e4[3];
;         }
;       }
.Lgs4_nochain:
	s_waitcnt lgkmcnt(8)
	v_mfma_f32_32x32x16_bf16 v[0:15], v[68:71], v[84:87], v[0:15]
	ds_read_b128 v[178:181], v252 offset:0
	ds_read_b128 v[182:185], v252 offset:32
	ds_read_b128 v[186:189], v252 offset:64
	ds_read_b128 v[190:193], v252 offset:96
	global_load_dwordx4 v[96:99], v134, s[6:7]
	global_load_dwordx4 v[100:103], v134, s[6:7] offset:128
	global_load_dwordx4 v[104:107], v134, s[8:9]
	global_load_dwordx4 v[108:111], v134, s[8:9] offset:128
	global_load_dwordx4 v[136:139], v135, s[10:11]
	global_load_dword v133, v145, s[18:19]
	s_waitcnt lgkmcnt(8)
	v_mfma_f32_32x32x16_bf16 v[0:15], v[72:75], v[88:91], v[0:15]
	s_waitcnt lgkmcnt(4)
	v_mfma_f32_32x32x16_bf16 v[0:15], v[76:79], v[92:95], v[0:15]
	s_nop 7
	s_nop 7

; __device__ __forceinline__ void gla_scan_phase(const Params& p, int j, bool need_ctx, char* smem, int tid, int bid) {
;     ...
;       {
;         if (tid < 128) ebend[tid] = ebv;
;         const int r = tid >> 3, c0 = tid & 7;
;         *(u32x4*)(qbL + swz256(r, c0)) = qx[0]; *(u32x4*)(qbL + swz256(r, c0 + 8)) = qx[1];
;         *(u32x4*)(kinvL + swz256(r, c0)) = kx[0]; *(u32x4*)(kinvL + swz256(r, c0 + 8)) = kx[1];
;         const int kdt = tid & 127, tgk = tid >> 7;
;         u32x4 w0 = {kt[0] | (kt[1] << 16), kt[2] | (kt[3] << 16), kt[4] | (kt[5] << 16), kt[6] | (kt[7] << 16)};
;         u32x4 w1 = {kt[8] | (kt[9] << 16), kt[10] | (kt[11] << 16), kt[12] | (kt[13] << 16), kt[14] | (kt[15] << 16)};
;         *(u32x4*)(kendT + swz128(kdt, tgk)) = w0;
;         *(u32x4*)(kendT + swz128(kdt, tgk + 4)) = w1;
;         u32x4 wv = {vv[0] | (vv[1] << 16), vv[2] | (vv[3] << 16), vv[4] | (vv[5] << 16), vv[6] | (vv[7] << 16)};
;         *(u32x4*)(vT + swz128(dvc, tg)) = wv;
;       }
.Lgs4_wd:
	ds_write_b128 v194, v[222:225] offset:40960
	ds_write_b128 v195, v[226:229] offset:40960
	ds_write_b128 v143, v[230:233] offset:57344
	ds_write_b128 v144, v[234:237] offset:57344
	ds_write_b128 v196, v[244:247] offset:40960
	s_cmp_gt_u32 s81, 1
	s_cbranch_scc1 .Lgs_noeb_b4
	ds_write_b32 v197, v248 offset:512

; __device__ __forceinline__ void gla_scan_phase(const Params& p, int j, bool need_ctx, char* smem, int tid, int bid) {
;     ...
;       if (!need_o) {
;       } else if (wid < 4) {
;         const int sb = wid & 1, tb = wid >> 1;
;         if (sb <= tb) {
;           f32x16 sacc;
; #pragma unroll
;           for (int r = 0; r < 16; ++r) sacc[r] = 0.f;
;           bf16x8 av[8], bv8[8];
; #pragma unroll
;           for (int k16 = 0; k16 < 8; ++k16) {
;             av[k16] = *(const bf16x8*)(kinvL + swz256(sb * 32 + l32, k16 * 2 + hi));
;             bv8[k16] = *(const bf16x8*)(qbL + swz256(tb * 32 + l32, k16 * 2 + hi));
;           }
; #pragma unroll
;           for (int k16 = 0; k16 < 8; ++k16) sacc = __builtin_amdgcn_mfma_f32_32x32x16_bf16(av[k16], bv8[k16], sacc, 0, 0, 0);
;           const int t = tb * 32 + l32;
; #pragma unroll
;           for (int rg = 0; rg < 4; ++rg) {
;             const int s0 = sb * 32 + 8 * rg + 4 * hi;
;             const float v0 = (s0 + 0 <= t) ? sacc[rg * 4 + 0] : 0.f, v1 = (s0 + 1 <= t) ? sacc[rg * 4 + 1] : 0.f;
;             const float v2 = (s0 + 2 <= t) ? sacc[rg * 4 + 2] : 0.f, v3 = (s0 + 3 <= t) ? sacc[rg * 4 + 3] : 0.f;
;             u32x2 w = {cvtpk(v0, v1), cvtpk(v2, v3)};
;             *(u32x2*)(scL + swz128(t, s0 >> 3) + (s0 & 7) * 2) = w;
;           }
;         }
;       } else {
;         bf16x8 av[8], bv8[8];
; #pragma unroll
;         for (int k16 = 0; k16 < 8; ++k16) {
;           av[k16] = *(const bf16x8*)(qbL + swz256(tbo * 32 + l32, k16 * 2 + hi));
;           bv8[k16] = *(const bf16x8*)(STL + swz256(dvbo * 32 + l32, k16 * 2 + hi));
;         }
; #pragma unroll
;         for (int k16 = 0; k16 < 8; ++k16) oacc = __builtin_amdgcn_mfma_f32_32x32x16_bf16(av[k16], bv8[k16], oacc, 0, 0, 0);
;       }
;       const int kb = wid >> 1, dvb2 = wid & 1;
;       {
;         bf16x8 av[4], bv4[4];
; #pragma unroll
;         for (int k16 = 0; k16 < 4; ++k16) {
;           av[k16] = *(const bf16x8*)(kendT + swz128(kb * 32 + l32, k16 * 2 + hi));
;           bv4[k16] = *(const bf16x8*)(vT + swz128(dvb2 * 32 + l32, k16 * 2 + hi));
;         }
; #pragma unroll
;         for (int k16 = 0; k16 < 4; ++k16) Sacc = __builtin_amdgcn_mfma_f32_32x32x16_bf16(av[k16], bv4[k16], Sacc, 0, 0, 0);
; #pragma unroll
;         for (int rg = 0; rg < 4; ++rg) {
;           const f32x4 e4 = *(const f32x4*)(ebend + kb * 32 + 8 * rg + 4 * hi);
.Lgs5_chunk:
	s_cmp_gt_u32 s54, 3
	s_cselect_b32 s96, 1, s60
	s_waitcnt lgkmcnt(0)
	s_barrier
	ds_read_b64_tr_b16 v[64:65], v140 offset:40960
	ds_read_b64_tr_b16 v[66:67], v141 offset:40960
	ds_read_b64_tr_b16 v[162:163], v142 offset:40960
	ds_read_b64_tr_b16 v[164:165], v142 offset:41472
	ds_read_b64_tr_b16 v[68:69], v140 offset:45056
	ds_read_b64_tr_b16 v[70:71], v141 offset:45056
	ds_read_b64_tr_b16 v[166:167], v142 offset:43008
	ds_read_b64_tr_b16 v[168:169], v142 offset:43520
	ds_read_b64_tr_b16 v[72:73], v140 offset:49152
	ds_read_b64_tr_b16 v[74:75], v141 offset:49152
	ds_read_b64_tr_b16 v[170:171], v142 offset:45056
	ds_read_b64_tr_b16 v[172:173], v142 offset:45568
	s_add_u32 s65, s54, 3
	s_min_u32 s65, s65, 67
	s_add_i32 s1, s65, -4
	s_cmp_lt_u32 s65, 4
	s_cselect_b32 s0, s65, s1
	s_movk_i32 s5, 0x1000
	s_cselect_b32 s1, 0x100, s5
	s_lshl_b32 s4, s35, 8
	s_add_u32 s4, s4, 0x8000
	s_lshl_b32 s5, s35, 12
	s_cmp_lt_u32 s65, 4
	s_cselect_b32 s4, s4, s5
	s_lshl_b32 s0, s0, 6
	s_sub_u32 s1, s1, 64
	s_sub_u32 s1, s1, s0
	s_cmp_eq_u32 s55, 0
	s_cselect_b32 s0, s0, s1
	s_add_u32 s0, s4, s0
	s_mul_i32 s1, s0, s34
	s_add_u32 s6, s22, s1
	s_addc_u32 s7, s23, 0
	s_add_u32 s8, s24, s1
	s_addc_u32 s9, s25, 0
	s_mul_i32 s1, s0, 0x1840
	s_add_u32 s10, s26, s1
	s_addc_u32 s11, s27, 0
	s_lshr_b32 s1, s0, 6
	s_lshl_b32 s1, s1, 11
	s_add_u32 s18, s28, s1
	s_addc_u32 s19, s29, 0
	s_waitcnt lgkmcnt(8)
	v_mfma_f32_32x32x16_bf16 v[0:15], v[64:67], v[162:165], v[0:15]
	ds_read_b64_tr_b16 v[76:77], v140 offset:53248
	ds_read_b64_tr_b16 v[78:79], v141 offset:53248
	ds_read_b64_tr_b16 v[174:175], v142 offset:47104
	ds_read_b64_tr_b16 v[176:177], v142 offset:47616
	s_cmp_eq_u32 s96, 0
	s_cbranch_scc1 .Lgs5_nochain
	s_cmp_eq_u32 s76, 1
	s_cbranch_scc1 .Lgs5_nochain
	s_waitcnt lgkmcnt(8)
	v_mfma_f32_32x32x16_bf16 v[0:15], v[68:71], v[166:169], v[0:15]
	ds_read_b128 v[32:35], v220
	ds_read_b128 v[48:51], v221 offset:40960
	v_xor_b32_e32 v198, 32, v220
	v_xor_b32_e32 v199, 32, v221
	ds_read_b128 v[36:39], v198
	ds_read_b128 v[52:55], v199 offset:40960
	global_load_dwordx4 v[222:225], v134, s[6:7]
	s_waitcnt lgkmcnt(8)
	v_mfma_f32_32x32x16_bf16 v[0:15], v[72:75], v[170:173], v[0:15]
	v_xor_b32_e32 v198, 64, v220
	v_xor_b32_e32 v199, 64, v221
	ds_read_b128 v[40:43], v198
	ds_read_b128 v[56:59], v199 offset:40960
	v_xor_b32_e32 v198, 96, v220
	v_xor_b32_e32 v199, 96, v221
	ds_read_b128 v[44:47], v198
	ds_read_b128 v[60:63], v199 offset:40960
	global_load_dwordx4 v[226:229], v134, s[6:7] offset:128
	s_waitcnt lgkmcnt(8)
	v_mfma_f32_32x32x16_bf16 v[0:15], v[76:79], v[174:177], v[0:15]
	global_load_dwordx4 v[230:233], v134, s[8:9]
	s_waitcnt lgkmcnt(6)
	v_mfma_f32_32x32x16_bf16 v[146:161], v[32:35], v[48:51], 0
	v_xor_b32_e32 v198, 128, v220
	v_xor_b32_e32 v199, 128, v221
	ds_read_b128 v[32:35], v198
	ds_read_b128 v[48:51], v199 offset:40960
	global_load_dwordx4 v[234:237], v134, s[8:9] offset:128
	s_waitcnt lgkmcnt(6)
	v_mfma_f32_32x32x16_bf16 v[146:161], v[36:39], v[52:55], v[146:161]
	v_xor_b32_e32 v198, 160, v220
	v_xor_b32_e32 v199, 160, v221
	ds_read_b128 v[36:39], v198
	ds_read_b128 v[52:55], v199 offset:40960
	global_load_dwordx4 v[244:247], v135, s[10:11]
	s_waitcnt lgkmcnt(6)
	v_mfma_f32_32x32x16_bf16 v[146:161], v[40:43], v[56:59], v[146:161]
	v_xor_b32_e32 v198, 192, v220
	v_xor_b32_e32 v199, 192, v221
	ds_read_b128 v[40:43], v198
	ds_read_b128 v[56:59], v199 offset:40960
	global_load_dword v248, v145, s[18:19]
	s_waitcnt lgkmcnt(6)
	v_mfma_f32_32x32x16_bf16 v[146:161], v[44:47], v[60:63], v[146:161]
	v_xor_b32_e32 v198, 224, v220
	v_xor_b32_e32 v199, 224, v221
	ds_read_b128 v[44:47], v198
	ds_read_b128 v[60:63], v199 offset:40960
	s_waitcnt lgkmcnt(6)
	v_mfma_f32_32x32x16_bf16 v[146:161], v[32:35], v[48:51], v[146:161]
	ds_read_b128 v[178:181], v252 offset:512
	ds_read_b128 v[182:185], v252 offset:544
	ds_read_b128 v[186:189], v252 offset:576
	ds_read_b128 v[190:193], v252 offset:608
	s_waitcnt lgkmcnt(8)
	v_mfma_f32_32x32x16_bf16 v[146:161], v[36:39], v[52:55], v[146:161]
	s_waitcnt lgkmcnt(6)
	v_mfma_f32_32x32x16_bf16 v[146:161], v[40:43], v[56:59], v[146:161]
	s_waitcnt lgkmcnt(4)
	v_mfma_f32_32x32x16_bf16 v[146:161], v[44:47], v[60:63], v[146:161]
	s_cmp_eq_u32 s16, 0
	s_cbranch_scc1 .Lgs5_scale
	s_cmp_eq_u32 s76, 2
	s_cbranch_scc0 .Lgs5_scale
	v_xor_b32_e32 v198, 32, v249
	ds_read_b128 v[64:67], v249 offset:0
	ds_read_b128 v[68:71], v198 offset:0
	s_cmp_eq_u32 s77, 0
	s_cbranch_scc1 .Lgs5_ohalf
	v_xor_b32_e32 v199, 64, v249
	v_xor_b32_e32 v200, 96, v249
	ds_read_b128 v[72:75], v199 offset:0
	ds_read_b128 v[76:79], v200 offset:0
	s_waitcnt lgkmcnt(2)
	v_mfma_f32_32x32x16_bf16 v[16:31], v[80:83], v[64:67], v[16:31]
	v_mfma_f32_32x32x16_bf16 v[16:31], v[84:87], v[68:71], v[16:31]
	s_waitcnt lgkmcnt(0)
	v_mfma_f32_32x32x16_bf16 v[16:31], v[88:91], v[72:75], v[16:31]
	v_mfma_f32_32x32x16_bf16 v[16:31], v[92:95], v[76:79], v[16:31]
	s_branch .Lgs5_odone

; __device__ __forceinline__ void gla_scan_phase(const Params& p, int j, bool need_ctx, char* smem, int tid, int bid) {
;     ...
;       const int kb = wid >> 1, dvb2 = wid & 1;
;       {
;         bf16x8 av[4], bv4[4];
; #pragma unroll
;         for (int k16 = 0; k16 < 4; ++k16) {
;           av[k16] = *(const bf16x8*)(kendT + swz128(kb * 32 + l32, k16 * 2 + hi));
;           bv4[k16] = *(const bf16x8*)(vT + swz128(dvb2 * 32 + l32, k16 * 2 + hi));
;         }
; #pragma unroll
;         for (int k16 = 0; k16 < 4; ++k16) Sacc = __builtin_amdgcn_mfma_f32_32x32x16_bf16(av[k16], bv4[k16], Sacc, 0, 0, 0);
; #pragma unroll
;         for (int rg = 0; rg < 4; ++rg) {
;           const f32x4 e4 = *(const f32x4*)(ebend + kb * 32 + 8 * rg + 4 * hi);
;           Sacc[rg * 4 + 0] *= e4[0]; Sacc[rg * 4 + 1] *= e4[1]; Sacc[rg * 4 + 2] *= e4[2]; Sacc[rg * 4 + 3] *= e4[3];
;         }
;       }
.Lgs5_nochain:
	s_waitcnt lgkmcnt(8)
	v_mfma_f32_32x32x16_bf16 v[0:15], v[68:71], v[166:169], v[0:15]
	ds_read_b128 v[178:181], v252 offset:512
	ds_read_b128 v[182:185], v252 offset:544
	ds_read_b128 v[186:189], v252 offset:576
	ds_read_b128 v[190:193], v252 offset:608
	global_load_dwordx4 v[222:225], v134, s[6:7]
	global_load_dwordx4 v[226:229], v134, s[6:7] offset:128
	global_load_dwordx4 v[230:233], v134, s[8:9]
	global_load_dwordx4 v[234:237], v134, s[8:9] offset:128
	global_load_dwordx4 v[244:247], v135, s[10:11]
	global_load_dword v248, v145, s[18:19]
	s_waitcnt lgkmcnt(8)
	v_mfma_f32_32x32x16_bf16 v[0:15], v[72:75], v[170:173], v[0:15]
	s_waitcnt lgkmcnt(4)
	v_mfma_f32_32x32x16_bf16 v[0:15], v[76:79], v[174:177], v[0:15]
	s_nop 7
	s_nop 7

; __device__ __forceinline__ void gla_scan_phase(const Params& p, int j, bool need_ctx, char* smem, int tid, int bid) {
;     ...
;       {
;         if (tid < 128) ebend[tid] = ebv;
;         const int r = tid >> 3, c0 = tid & 7;
;         *(u32x4*)(qbL + swz256(r, c0)) = qx[0]; *(u32x4*)(qbL + swz256(r, c0 + 8)) = qx[1];
;         *(u32x4*)(kinvL + swz256(r, c0)) = kx[0]; *(u32x4*)(kinvL + swz256(r, c0 + 8)) = kx[1];
;         const int kdt = tid & 127, tgk = tid >> 7;
;         u32x4 w0 = {kt[0] | (kt[1] << 16), kt[2] | (kt[3] << 16), kt[4] | (kt[5] << 16), kt[6] | (kt[7] << 16)};
;         u32x4 w1 = {kt[8] | (kt[9] << 16), kt[10] | (kt[11] << 16), kt[12] | (kt[13] << 16), kt[14] | (kt[15] << 16)};
;         *(u32x4*)(kendT + swz128(kdt, tgk)) = w0;
;         *(u32x4*)(kendT + swz128(kdt, tgk + 4)) = w1;
;         u32x4 wv = {vv[0] | (vv[1] << 16), vv[2] | (vv[3] << 16), vv[4] | (vv[5] << 16), vv[6] | (vv[7] << 16)};
;         *(u32x4*)(vT + swz128(dvc, tg)) = wv;
;       }
.Lgs5_wd:
	ds_write_b128 v194, v[112:115] offset:0
	ds_write_b128 v195, v[116:119] offset:0
	ds_write_b128 v143, v[120:123] offset:16384
	ds_write_b128 v144, v[124:127] offset:16384
	ds_write_b128 v196, v[128:131] offset:0
	s_cmp_gt_u32 s81, 1
	s_cbranch_scc1 .Lgs_noeb_b5
	ds_write_b32 v197, v132 offset:0

; __device__ __forceinline__ void gla_scan_phase(const Params& p, int j, bool need_ctx, char* smem, int tid, int bid) {
;     ...
;       if (wid >= 4 && need_o) {
; #pragma unroll
;         for (int k16 = 0; k16 < 4; ++k16) {
;           if (k16 < 2 || tbo == 1) {
;             const bf16x8 a = *(const bf16x8*)(scL + swz128(tbo * 32 + l32, k16 * 2 + hi));
;             const bf16x8 bv = *(const bf16x8*)(vT + swz128(dvbo * 32 + l32, k16 * 2 + hi));
;             oacc = __builtin_amdgcn_mfma_f32_32x32x16_bf16(a, bv, oacc, 0, 0, 0);
;           }
;         }
.Lgs5_next:
	s_mov_b32 s16, s96
	s_add_u32 s54, s54, 1
	s_branch .Lgs_pair
.Lgs_tail:
	s_cmp_eq_u32 s76, 2
	s_cbranch_scc0 .Lgs_unit_end
	v_xor_b32_e32 v198, 32, v249
	ds_read_b128 v[64:67], v249 offset:8192
	ds_read_b128 v[68:71], v198 offset:8192
	s_cmp_eq_u32 s77, 0
	s_cbranch_scc1 .Lgs_t_ohalf
	v_xor_b32_e32 v199, 64, v249
	v_xor_b32_e32 v200, 96, v249
	ds_read_b128 v[72:75], v199 offset:8192
	ds_read_b128 v[76:79], v200 offset:8192
	s_waitcnt lgkmcnt(2)
	v_mfma_f32_32x32x16_bf16 v[146:161], v[162:165], v[64:67], v[146:161]
	v_mfma_f32_32x32x16_bf16 v[146:161], v[166:169], v[68:71], v[146:161]
	s_waitcnt lgkmcnt(0)
	v_mfma_f32_32x32x16_bf16 v[146:161], v[170:173], v[72:75], v[146:161]
	v_mfma_f32_32x32x16_bf16 v[146:161], v[174:177], v[76:79], v[146:161]
	s_branch .Lgs_t_odone

; __device__ __forceinline__ u16 f2bf(float x) { return (u16)(cvtpk(x, 0.f) & 0xffffu); }
; __device__ __forceinline__ int crow(int r, int hi) { return (r & 3) + 8 * (r >> 2) + 4 * hi; }
; __device__ __forceinline__ void gla_scan_phase(const Params& p, int j, bool need_ctx, char* smem, int tid, int bid) {
;     ...
;         if (!is_ctx || need_ctx) {
;           u16* O = dir ? OB : OF;
; #pragma unroll
;           for (int r = 0; r < 16; ++r) {
;             const int pos = c * 64 + tbo * 32 + crow(r, hi);
;             const int tok = dir ? TT - 1 - pos : pos;
;             O[(size_t)(base + tok) * 1024 + h * 256 + dvs * 64 + dvbo * 32 + l32] = f2bf(oacc[r]);
;           }
;         }
;       }
;       {
;         const int dv = dvb2 * 32 + l32;
; #pragma unroll
;         for (int rg = 0; rg < 4; ++rg) {
;           const int k0 = kb * 32 + 8 * rg + 4 * hi;
;           u32x2 w = {cvtpk(Sacc[rg * 4 + 0], Sacc[rg * 4 + 1]), cvtpk(Sacc[rg * 4 + 2], Sacc[rg * 4 + 3])};
;           *(u32x2*)(STL + swz256(dv, k0 >> 3) + (k0 & 7) * 2) = w;
;         }
;       }
;     }
;     ...
;     __syncthreads();
;   }
.Lgs_t_odone:
	s_nop 7
	s_nop 7
	s_add_i32 s65, s54, -1
	s_add_i32 s1, s65, -4
	s_cmp_lt_u32 s65, 4
	s_cselect_b32 s0, s65, s1
	s_movk_i32 s5, 0x1000
	s_cselect_b32 s1, 0x100, s5
	s_lshl_b32 s4, s35, 8
	s_add_u32 s4, s4, 0x8000
	s_lshl_b32 s5, s35, 12
	s_cmp_lt_u32 s65, 4
	s_cselect_b32 s4, s4, s5
	s_lshl_b32 s0, s0, 6
	s_sub_u32 s1, s1, 64
	s_sub_u32 s1, s1, s0
	s_cmp_eq_u32 s55, 0
	s_cselect_b32 s0, s0, s1
	s_add_u32 s0, s4, s0
	s_lshl_b32 s1, s0, 11
	s_add_u32 s20, s30, s1
	s_addc_u32 s21, s31, 0
	v_cvt_pk_bf16_f32 v186, v146, v147
	v_cvt_pk_bf16_f32 v187, v148, v149
	v_cvt_pk_bf16_f32 v188, v150, v151
	v_cvt_pk_bf16_f32 v189, v152, v153
	v_cvt_pk_bf16_f32 v190, v154, v155
	v_cvt_pk_bf16_f32 v191, v156, v157
	v_cvt_pk_bf16_f32 v192, v158, v159
	v_cvt_pk_bf16_f32 v193, v160, v161
	s_nop 0
	v_permlane32_swap_b32_e32 v186, v188
	v_permlane32_swap_b32_e32 v187, v189
	v_permlane32_swap_b32_e32 v190, v192
	v_permlane32_swap_b32_e32 v191, v193
	global_store_dwordx4 v204, v[186:189], s[20:21]
	global_store_dwordx4 v204, v[190:193], s[20:21] offset:32
.Lgs_unit_end:
	s_waitcnt vmcnt(0) lgkmcnt(0)
	s_barrier
	s_add_i32 s53, s53, s71
	s_cmpk_gt_i32 s53, 0xff
	s_cbranch_scc0 .Lgs_unit
